# mid-burst s_setprio 0 / s_setprio 1 pairs removed from the GEMM K-loops (A/B of the per-phase priority flips)
# speedup vs baseline: 1.0054x; 1.0054x over previous
; #define PG8_STAGE(bufoff, gbase, voff) do { _Pragma("unroll") for (int _i = 0; _i < 2; ++_i) \
;         __builtin_amdgcn_global_load_lds((const unsigned*)((const char*)(gbase) + (voff)[_i]), (PG8_LAS unsigned*)(lds + (bufoff) + ldsw + _i * 8192), 16, 0, 0); } while (0)
; #define PG8_LDA(dst, b, h) do { _Pragma("unroll") for (int m = 0; m < 4; ++m) _Pragma("unroll") for (int k = 0; k < 2; ++k) dst[m][k] = *(const PG8_LAS bf16x8*)(lds + PG8_SA(b, h) + aoff + m * 2048 + k * 1024); } while (0)
; #define PG8_LDB(dst, b, h) do { _Pragma("unroll") for (int n = 0; n < 2; ++n) _Pragma("unroll") for (int k = 0; k < 2; ++k) dst[n][k] = *(const PG8_LAS bf16x8*)(lds + PG8_SB(b, h) + boff + n * 2048 + k * 1024); } while (0)
; #define PG8_MMA(ai, bj, At, Bt) do { __builtin_amdgcn_s_setprio(1); _Pragma("unroll") for (int m = 0; m < 4; ++m) _Pragma("unroll") for (int n = 0; n < 2; ++n) _Pragma("unroll") for (int k = 0; k < 2; ++k) \
;         acc[ai][bj][m][n] = __builtin_amdgcn_mfma_f32_16x16x32_bf16(Bt[n][k], At[m][k], acc[ai][bj][m][n], 0, 0, 0); __builtin_amdgcn_s_setprio(0); } while (0)
; #define PG8_WAIT_V(n) asm volatile("s_waitcnt vmcnt(" #n ")" ::: "memory")
; #define PG8_WAIT_L(n) asm volatile("s_waitcnt lgkmcnt(" #n ")" ::: "memory")
; #define PG8_BAR __builtin_amdgcn_s_barrier()
; #define PG8_SCHED __builtin_amdgcn_sched_barrier(0)
; template <class Epi, class Sched, bool ALIGN_EPI = false, bool SP2 = false>
; __device__ __forceinline__ void gemm_phase(PG8_LAS unsigned char* lds, const Gemm g, const Sched& S, const Epi& E) {
;     ...
;             PG8_LDB(B0, 0, 0); PG8_LDB(B1, 0, 1); PG8_SCHED; PG8_LDA(At, 0, 0); PG8_STAGE(PG8_SA(1, 1), a1 + hstepA, voffA);
;             PG8_WAIT_V(8); PG8_WAIT_L(0); PG8_BAR; PG8_MMA(0, 0, At, B0); PG8_MMA(0, 1, At, B1); PG8_BAR; PG8_SCHED;
;             PG8_LDA(At, 0, 1); PG8_STAGE(PG8_SB(0, 0), b2, voffB); PG8_STAGE(PG8_SB(0, 1), b2 + hstepB, voffB); PG8_STAGE(PG8_SA(0, 0), a2, voffA);
;             PG8_WAIT_V(8); PG8_WAIT_L(0); PG8_BAR; PG8_MMA(1, 0, At, B0); PG8_MMA(1, 1, At, B1); PG8_BAR; PG8_SCHED;
.LBB0_157:
	v_add_u32_e32 v136, s2, v139
	ds_read_b128 v[186:189], v136
	ds_read_b128 v[190:193], v136 offset:1024
	ds_read_b128 v[194:197], v136 offset:2048
	ds_read_b128 v[198:201], v136 offset:3072
	v_add_u32_e32 v136, s3, v139
	ds_read_b128 v[202:205], v136
	ds_read_b128 v[206:209], v136 offset:1024
	ds_read_b128 v[210:213], v136 offset:2048
	ds_read_b128 v[214:217], v136 offset:3072
	s_add_u32 s38, s36, 0xfffc0080
	s_addc_u32 s39, s37, -1
	s_cmp_eq_u32 s45, 12
	s_cselect_b32 s41, s7, s39
	s_cselect_b32 s40, s29, s38
	s_cselect_b32 s39, s27, s44
	s_cselect_b32 s38, s42, s43
	v_lshl_add_u64 v[250:251], s[36:37], 0, v[178:179]
	s_add_i32 m0, s63, 0xc000
	ds_read_b128 v[218:221], v159
	ds_read_b128 v[222:225], v159 offset:1024
	ds_read_b128 v[226:229], v159 offset:2048
	ds_read_b128 v[230:233], v159 offset:3072
	ds_read_b128 v[234:237], v159 offset:4096
	ds_read_b128 v[238:241], v159 offset:5120
	ds_read_b128 v[242:245], v159 offset:6144
	ds_read_b128 v[246:249], v159 offset:7168
	global_load_lds_dwordx4 v[250:251], off
	v_lshl_add_u64 v[250:251], s[36:37], 0, v[180:181]
	s_add_i32 m0, s63, 0xe000
	s_nop 0
	global_load_lds_dwordx4 v[250:251], off
	s_waitcnt vmcnt(8)
	s_waitcnt lgkmcnt(0)
	s_barrier
	s_setprio 1
	s_waitcnt lgkmcnt(0)
	v_mfma_f32_16x16x32_bf16 v[124:127], v[186:189], v[218:221], v[124:127]
	v_mfma_f32_16x16x32_bf16 v[120:123], v[194:197], v[218:221], v[120:123]
	v_mfma_f32_16x16x32_bf16 v[108:111], v[186:189], v[226:229], v[108:111]
	v_mfma_f32_16x16x32_bf16 v[104:107], v[194:197], v[226:229], v[104:107]
	v_mfma_f32_16x16x32_bf16 v[92:95], v[186:189], v[234:237], v[92:95]
	v_mfma_f32_16x16x32_bf16 v[88:91], v[194:197], v[234:237], v[88:91]
	v_mfma_f32_16x16x32_bf16 v[76:79], v[186:189], v[242:245], v[76:79]
	v_mfma_f32_16x16x32_bf16 v[72:75], v[194:197], v[242:245], v[72:75]
	v_mfma_f32_16x16x32_bf16 v[124:127], v[190:193], v[222:225], v[124:127]
	v_mfma_f32_16x16x32_bf16 v[120:123], v[198:201], v[222:225], v[120:123]
	v_mfma_f32_16x16x32_bf16 v[108:111], v[190:193], v[230:233], v[108:111]
	v_mfma_f32_16x16x32_bf16 v[104:107], v[198:201], v[230:233], v[104:107]
	v_mfma_f32_16x16x32_bf16 v[92:95], v[190:193], v[238:241], v[92:95]
	v_mfma_f32_16x16x32_bf16 v[88:91], v[198:201], v[238:241], v[88:91]
	v_mfma_f32_16x16x32_bf16 v[76:79], v[190:193], v[246:249], v[76:79]
	v_mfma_f32_16x16x32_bf16 v[72:75], v[198:201], v[246:249], v[72:75]
	v_mfma_f32_16x16x32_bf16 v[116:119], v[202:205], v[218:221], v[116:119]
	v_mfma_f32_16x16x32_bf16 v[112:115], v[210:213], v[218:221], v[112:115]
	v_mfma_f32_16x16x32_bf16 v[100:103], v[202:205], v[226:229], v[100:103]
	v_mfma_f32_16x16x32_bf16 v[96:99], v[210:213], v[226:229], v[96:99]
	v_mfma_f32_16x16x32_bf16 v[84:87], v[202:205], v[234:237], v[84:87]
	v_mfma_f32_16x16x32_bf16 v[80:83], v[210:213], v[234:237], v[80:83]
	v_mfma_f32_16x16x32_bf16 v[68:71], v[202:205], v[242:245], v[68:71]
	v_mfma_f32_16x16x32_bf16 v[64:67], v[210:213], v[242:245], v[64:67]
	v_mfma_f32_16x16x32_bf16 v[116:119], v[206:209], v[222:225], v[116:119]
	v_mfma_f32_16x16x32_bf16 v[112:115], v[214:217], v[222:225], v[112:115]
	v_mfma_f32_16x16x32_bf16 v[100:103], v[206:209], v[230:233], v[100:103]
	v_mfma_f32_16x16x32_bf16 v[96:99], v[214:217], v[230:233], v[96:99]
	v_mfma_f32_16x16x32_bf16 v[84:87], v[206:209], v[238:241], v[84:87]
	v_mfma_f32_16x16x32_bf16 v[80:83], v[214:217], v[238:241], v[80:83]
	v_mfma_f32_16x16x32_bf16 v[68:71], v[206:209], v[246:249], v[68:71]
	v_mfma_f32_16x16x32_bf16 v[64:67], v[214:217], v[246:249], v[64:67]
	s_setprio 0
	s_barrier
	s_add_i32 s46, s2, s62
	v_lshl_add_u64 v[250:251], s[38:39], 0, v[130:131]
	s_mov_b32 m0, s46
	ds_read_b128 v[218:221], v159 offset:16384
	ds_read_b128 v[222:225], v159 offset:17408
	ds_read_b128 v[226:229], v159 offset:18432
	ds_read_b128 v[230:233], v159 offset:19456
	ds_read_b128 v[234:237], v159 offset:20480
	ds_read_b128 v[238:241], v159 offset:21504
	ds_read_b128 v[242:245], v159 offset:22528
	ds_read_b128 v[246:249], v159 offset:23552
	global_load_lds_dwordx4 v[250:251], off
	s_add_i32 m0, s46, 0x2000
	s_add_u32 s46, s38, 0x40000
	v_lshl_add_u64 v[252:253], s[38:39], 0, v[134:135]
	s_addc_u32 s47, s39, 0
	s_add_i32 s48, s3, s62
	global_load_lds_dwordx4 v[252:253], off
	v_lshl_add_u64 v[166:167], s[46:47], 0, v[130:131]
	s_mov_b32 m0, s48
	v_lshl_add_u64 v[168:169], s[40:41], 0, v[132:133]
	global_load_lds_dwordx4 v[166:167], off
	v_lshl_add_u64 v[166:167], s[46:47], 0, v[134:135]
	s_add_i32 m0, s48, 0x2000
	s_nop 0
	global_load_lds_dwordx4 v[166:167], off
	v_lshl_add_u64 v[166:167], s[40:41], 0, v[128:129]
	s_mov_b32 m0, s63
	s_nop 0
	global_load_lds_dwordx4 v[166:167], off
	s_mov_b32 m0, s64
	s_nop 0
	global_load_lds_dwordx4 v[168:169], off
	s_waitcnt vmcnt(8)
	s_waitcnt lgkmcnt(0)
	s_barrier
; #define PG8_STAGE(bufoff, gbase, voff) do { _Pragma("unroll") for (int _i = 0; _i < 2; ++_i) \
;         __builtin_amdgcn_global_load_lds((const unsigned*)((const char*)(gbase) + (voff)[_i]), (PG8_LAS unsigned*)(lds + (bufoff) + ldsw + _i * 8192), 16, 0, 0); } while (0)
; #define PG8_LDA(dst, b, h) do { _Pragma("unroll") for (int m = 0; m < 4; ++m) _Pragma("unroll") for (int k = 0; k < 2; ++k) dst[m][k] = *(const PG8_LAS bf16x8*)(lds + PG8_SA(b, h) + aoff + m * 2048 + k * 1024); } while (0)
; #define PG8_LDB(dst, b, h) do { _Pragma("unroll") for (int n = 0; n < 2; ++n) _Pragma("unroll") for (int k = 0; k < 2; ++k) dst[n][k] = *(const PG8_LAS bf16x8*)(lds + PG8_SB(b, h) + boff + n * 2048 + k * 1024); } while (0)
; #define PG8_MMA(ai, bj, At, Bt) do { __builtin_amdgcn_s_setprio(1); _Pragma("unroll") for (int m = 0; m < 4; ++m) _Pragma("unroll") for (int n = 0; n < 2; ++n) _Pragma("unroll") for (int k = 0; k < 2; ++k) \
;         acc[ai][bj][m][n] = __builtin_amdgcn_mfma_f32_16x16x32_bf16(Bt[n][k], At[m][k], acc[ai][bj][m][n], 0, 0, 0); __builtin_amdgcn_s_setprio(0); } while (0)
; #define PG8_WAIT_V(n) asm volatile("s_waitcnt vmcnt(" #n ")" ::: "memory")
; #define PG8_WAIT_L(n) asm volatile("s_waitcnt lgkmcnt(" #n ")" ::: "memory")
; #define PG8_BAR __builtin_amdgcn_s_barrier()
; #define PG8_SCHED __builtin_amdgcn_sched_barrier(0)
; template <class Epi, class Sched, bool ALIGN_EPI = false, bool SP2 = false>
; __device__ __forceinline__ void gemm_phase(PG8_LAS unsigned char* lds, const Gemm g, const Sched& S, const Epi& E) {
;     ...
;             PG8_LDA(At, 0, 1); PG8_STAGE(PG8_SB(0, 0), b2, voffB); PG8_STAGE(PG8_SB(0, 1), b2 + hstepB, voffB); PG8_STAGE(PG8_SA(0, 0), a2, voffA);
;             PG8_WAIT_V(8); PG8_WAIT_L(0); PG8_BAR; PG8_MMA(1, 0, At, B0); PG8_MMA(1, 1, At, B1); PG8_BAR; PG8_SCHED;
;             PG8_LDB(B0, 1, 0); PG8_LDB(B1, 1, 1); PG8_SCHED; PG8_LDA(At, 1, 0); PG8_STAGE(PG8_SA(0, 1), a2 + hstepA, voffA);
;             PG8_WAIT_V(8); PG8_WAIT_L(0); PG8_BAR; PG8_MMA(0, 0, At, B0); PG8_MMA(0, 1, At, B1); PG8_BAR; PG8_SCHED;
	s_setprio 1
	s_waitcnt lgkmcnt(0)
	v_mfma_f32_16x16x32_bf16 v[60:63], v[186:189], v[218:221], v[60:63]
	v_mfma_f32_16x16x32_bf16 v[56:59], v[194:197], v[218:221], v[56:59]
	v_mfma_f32_16x16x32_bf16 v[44:47], v[186:189], v[226:229], v[44:47]
	v_mfma_f32_16x16x32_bf16 v[40:43], v[194:197], v[226:229], v[40:43]
	v_mfma_f32_16x16x32_bf16 v[28:31], v[186:189], v[234:237], v[28:31]
	v_mfma_f32_16x16x32_bf16 v[24:27], v[194:197], v[234:237], v[24:27]
	v_mfma_f32_16x16x32_bf16 v[12:15], v[186:189], v[242:245], v[12:15]
	v_mfma_f32_16x16x32_bf16 v[8:11], v[194:197], v[242:245], v[8:11]
	v_mfma_f32_16x16x32_bf16 v[60:63], v[190:193], v[222:225], v[60:63]
	v_mfma_f32_16x16x32_bf16 v[56:59], v[198:201], v[222:225], v[56:59]
	v_mfma_f32_16x16x32_bf16 v[44:47], v[190:193], v[230:233], v[44:47]
	v_mfma_f32_16x16x32_bf16 v[40:43], v[198:201], v[230:233], v[40:43]
	v_mfma_f32_16x16x32_bf16 v[28:31], v[190:193], v[238:241], v[28:31]
	v_mfma_f32_16x16x32_bf16 v[24:27], v[198:201], v[238:241], v[24:27]
	v_mfma_f32_16x16x32_bf16 v[12:15], v[190:193], v[246:249], v[12:15]
	v_mfma_f32_16x16x32_bf16 v[8:11], v[198:201], v[246:249], v[8:11]
	v_mfma_f32_16x16x32_bf16 v[52:55], v[202:205], v[218:221], v[52:55]
	v_mfma_f32_16x16x32_bf16 v[48:51], v[210:213], v[218:221], v[48:51]
	v_mfma_f32_16x16x32_bf16 v[36:39], v[202:205], v[226:229], v[36:39]
	v_mfma_f32_16x16x32_bf16 v[32:35], v[210:213], v[226:229], v[32:35]
	v_mfma_f32_16x16x32_bf16 v[20:23], v[202:205], v[234:237], v[20:23]
	v_mfma_f32_16x16x32_bf16 v[16:19], v[210:213], v[234:237], v[16:19]
	v_mfma_f32_16x16x32_bf16 v[4:7], v[202:205], v[242:245], v[4:7]
	v_mfma_f32_16x16x32_bf16 v[0:3], v[210:213], v[242:245], v[0:3]
	v_mfma_f32_16x16x32_bf16 v[52:55], v[206:209], v[222:225], v[52:55]
	v_mfma_f32_16x16x32_bf16 v[48:51], v[214:217], v[222:225], v[48:51]
	v_mfma_f32_16x16x32_bf16 v[36:39], v[206:209], v[230:233], v[36:39]
	v_mfma_f32_16x16x32_bf16 v[32:35], v[214:217], v[230:233], v[32:35]
	v_mfma_f32_16x16x32_bf16 v[20:23], v[206:209], v[238:241], v[20:23]
	v_mfma_f32_16x16x32_bf16 v[16:19], v[214:217], v[238:241], v[16:19]
	v_mfma_f32_16x16x32_bf16 v[4:7], v[206:209], v[246:249], v[4:7]
	v_mfma_f32_16x16x32_bf16 v[0:3], v[214:217], v[246:249], v[0:3]
	s_setprio 0
	s_barrier
	s_add_i32 s46, 0, 0x18000
	v_add_u32_e32 v136, s46, v139
	s_add_i32 s47, 0, 0x1c000
	ds_read_b128 v[186:189], v136
	ds_read_b128 v[190:193], v136 offset:1024
	ds_read_b128 v[194:197], v136 offset:2048
	ds_read_b128 v[198:201], v136 offset:3072
	v_add_u32_e32 v136, s47, v139
	ds_read_b128 v[202:205], v136
	ds_read_b128 v[206:209], v136 offset:1024
	ds_read_b128 v[210:213], v136 offset:2048
	ds_read_b128 v[214:217], v136 offset:3072
	s_add_u32 s40, s40, 0x40000
	s_addc_u32 s41, s41, 0
	s_mov_b32 m0, s65
	v_lshl_add_u64 v[170:171], s[40:41], 0, v[128:129]
	ds_read_b128 v[218:221], v159 offset:32768
	ds_read_b128 v[222:225], v159 offset:33792
	ds_read_b128 v[226:229], v159 offset:34816
	ds_read_b128 v[230:233], v159 offset:35840
	ds_read_b128 v[234:237], v159 offset:36864
	ds_read_b128 v[238:241], v159 offset:37888
	ds_read_b128 v[242:245], v159 offset:38912
	ds_read_b128 v[246:249], v159 offset:39936
	global_load_lds_dwordx4 v[170:171], off
	v_lshl_add_u64 v[170:171], s[40:41], 0, v[132:133]
	s_mov_b32 m0, s66
	s_nop 0
	global_load_lds_dwordx4 v[170:171], off
	s_waitcnt vmcnt(8)
	s_waitcnt lgkmcnt(0)
	s_barrier
	s_setprio 1
	s_waitcnt lgkmcnt(0)
	v_mfma_f32_16x16x32_bf16 v[124:127], v[186:189], v[218:221], v[124:127]
	v_mfma_f32_16x16x32_bf16 v[120:123], v[194:197], v[218:221], v[120:123]
	v_mfma_f32_16x16x32_bf16 v[108:111], v[186:189], v[226:229], v[108:111]
	v_mfma_f32_16x16x32_bf16 v[104:107], v[194:197], v[226:229], v[104:107]
	v_mfma_f32_16x16x32_bf16 v[92:95], v[186:189], v[234:237], v[92:95]
	v_mfma_f32_16x16x32_bf16 v[88:91], v[194:197], v[234:237], v[88:91]
	v_mfma_f32_16x16x32_bf16 v[76:79], v[186:189], v[242:245], v[76:79]
	v_mfma_f32_16x16x32_bf16 v[72:75], v[194:197], v[242:245], v[72:75]
	v_mfma_f32_16x16x32_bf16 v[124:127], v[190:193], v[222:225], v[124:127]
	v_mfma_f32_16x16x32_bf16 v[120:123], v[198:201], v[222:225], v[120:123]
	v_mfma_f32_16x16x32_bf16 v[108:111], v[190:193], v[230:233], v[108:111]
	v_mfma_f32_16x16x32_bf16 v[104:107], v[198:201], v[230:233], v[104:107]
	v_mfma_f32_16x16x32_bf16 v[92:95], v[190:193], v[238:241], v[92:95]
	v_mfma_f32_16x16x32_bf16 v[88:91], v[198:201], v[238:241], v[88:91]
	v_mfma_f32_16x16x32_bf16 v[76:79], v[190:193], v[246:249], v[76:79]
	v_mfma_f32_16x16x32_bf16 v[72:75], v[198:201], v[246:249], v[72:75]
	v_mfma_f32_16x16x32_bf16 v[116:119], v[202:205], v[218:221], v[116:119]
	v_mfma_f32_16x16x32_bf16 v[112:115], v[210:213], v[218:221], v[112:115]
	v_mfma_f32_16x16x32_bf16 v[100:103], v[202:205], v[226:229], v[100:103]
	v_mfma_f32_16x16x32_bf16 v[96:99], v[210:213], v[226:229], v[96:99]
	v_mfma_f32_16x16x32_bf16 v[84:87], v[202:205], v[234:237], v[84:87]
	v_mfma_f32_16x16x32_bf16 v[80:83], v[210:213], v[234:237], v[80:83]
	v_mfma_f32_16x16x32_bf16 v[68:71], v[202:205], v[242:245], v[68:71]
	v_mfma_f32_16x16x32_bf16 v[64:67], v[210:213], v[242:245], v[64:67]
	v_mfma_f32_16x16x32_bf16 v[116:119], v[206:209], v[222:225], v[116:119]
	v_mfma_f32_16x16x32_bf16 v[112:115], v[214:217], v[222:225], v[112:115]
	v_mfma_f32_16x16x32_bf16 v[100:103], v[206:209], v[230:233], v[100:103]
	v_mfma_f32_16x16x32_bf16 v[96:99], v[214:217], v[230:233], v[96:99]
	v_mfma_f32_16x16x32_bf16 v[84:87], v[206:209], v[238:241], v[84:87]
	v_mfma_f32_16x16x32_bf16 v[80:83], v[214:217], v[238:241], v[80:83]
	v_mfma_f32_16x16x32_bf16 v[68:71], v[206:209], v[246:249], v[68:71]
	v_mfma_f32_16x16x32_bf16 v[64:67], v[214:217], v[246:249], v[64:67]
	s_setprio 0
	s_barrier
; #define PG8_STAGE(bufoff, gbase, voff) do { _Pragma("unroll") for (int _i = 0; _i < 2; ++_i) \
;         __builtin_amdgcn_global_load_lds((const unsigned*)((const char*)(gbase) + (voff)[_i]), (PG8_LAS unsigned*)(lds + (bufoff) + ldsw + _i * 8192), 16, 0, 0); } while (0)
; #define PG8_LDA(dst, b, h) do { _Pragma("unroll") for (int m = 0; m < 4; ++m) _Pragma("unroll") for (int k = 0; k < 2; ++k) dst[m][k] = *(const PG8_LAS bf16x8*)(lds + PG8_SA(b, h) + aoff + m * 2048 + k * 1024); } while (0)
; #define PG8_LDB(dst, b, h) do { _Pragma("unroll") for (int n = 0; n < 2; ++n) _Pragma("unroll") for (int k = 0; k < 2; ++k) dst[n][k] = *(const PG8_LAS bf16x8*)(lds + PG8_SB(b, h) + boff + n * 2048 + k * 1024); } while (0)
; #define PG8_MMA(ai, bj, At, Bt) do { __builtin_amdgcn_s_setprio(1); _Pragma("unroll") for (int m = 0; m < 4; ++m) _Pragma("unroll") for (int n = 0; n < 2; ++n) _Pragma("unroll") for (int k = 0; k < 2; ++k) \
;         acc[ai][bj][m][n] = __builtin_amdgcn_mfma_f32_16x16x32_bf16(Bt[n][k], At[m][k], acc[ai][bj][m][n], 0, 0, 0); __builtin_amdgcn_s_setprio(0); } while (0)
; #define PG8_WAIT_V(n) asm volatile("s_waitcnt vmcnt(" #n ")" ::: "memory")
; #define PG8_WAIT_L(n) asm volatile("s_waitcnt lgkmcnt(" #n ")" ::: "memory")
; #define PG8_BAR __builtin_amdgcn_s_barrier()
; #define PG8_SCHED __builtin_amdgcn_sched_barrier(0)
; template <class Epi, class Sched, bool ALIGN_EPI = false, bool SP2 = false>
; __device__ __forceinline__ void gemm_phase(PG8_LAS unsigned char* lds, const Gemm g, const Sched& S, const Epi& E) {
;     ...
;         for (int t = 0; t < nt; t += 2) {
;     ...
;             PG8_LDB(B0, 1, 0); PG8_LDB(B1, 1, 1); PG8_SCHED; PG8_LDA(At, 1, 0); PG8_STAGE(PG8_SA(0, 1), a2 + hstepA, voffA);
;             PG8_WAIT_V(8); PG8_WAIT_L(0); PG8_BAR; PG8_MMA(0, 0, At, B0); PG8_MMA(0, 1, At, B1); PG8_BAR; PG8_SCHED;
;             PG8_LDA(At, 1, 1); PG8_STAGE(PG8_SB(1, 0), b3, voffB); PG8_STAGE(PG8_SB(1, 1), b3 + hstepB, voffB); PG8_STAGE(PG8_SA(1, 0), a3, voffA);
;             PG8_WAIT_V(8); PG8_WAIT_L(0); PG8_BAR; PG8_MMA(1, 0, At, B0); PG8_MMA(1, 1, At, B1); PG8_BAR; PG8_SCHED;
	s_add_i32 s40, s46, s62
	v_lshl_add_u64 v[170:171], v[250:251], 0, s[22:23]
	s_mov_b32 m0, s40
	ds_read_b128 v[218:221], v159 offset:49152
	ds_read_b128 v[222:225], v159 offset:50176
	ds_read_b128 v[226:229], v159 offset:51200
	ds_read_b128 v[230:233], v159 offset:52224
	ds_read_b128 v[234:237], v159 offset:53248
	ds_read_b128 v[238:241], v159 offset:54272
	ds_read_b128 v[242:245], v159 offset:55296
	ds_read_b128 v[246:249], v159 offset:56320
	global_load_lds_dwordx4 v[170:171], off
	s_add_i32 m0, s40, 0x2000
	s_add_u32 s38, s38, 0x40080
	v_lshl_add_u64 v[170:171], v[252:253], 0, s[22:23]
	s_addc_u32 s39, s39, 0
	s_add_i32 s40, s47, s62
	global_load_lds_dwordx4 v[170:171], off
	v_lshl_add_u64 v[170:171], s[38:39], 0, v[130:131]
	s_mov_b32 m0, s40
	v_lshl_add_u64 v[166:167], v[166:167], 0, s[22:23]
	global_load_lds_dwordx4 v[170:171], off
	v_lshl_add_u64 v[170:171], s[38:39], 0, v[134:135]
	s_add_i32 m0, s40, 0x2000
	s_nop 0
	global_load_lds_dwordx4 v[170:171], off
	s_mov_b32 m0, s93
	s_nop 0
	global_load_lds_dwordx4 v[166:167], off
	v_lshl_add_u64 v[166:167], v[168:169], 0, s[22:23]
	s_mov_b32 m0, s96
	s_nop 0
	global_load_lds_dwordx4 v[166:167], off
	s_waitcnt vmcnt(8)
	s_waitcnt lgkmcnt(0)
	s_barrier
	s_setprio 1
	s_waitcnt lgkmcnt(0)
	v_mfma_f32_16x16x32_bf16 v[60:63], v[186:189], v[218:221], v[60:63]
	v_mfma_f32_16x16x32_bf16 v[56:59], v[194:197], v[218:221], v[56:59]
	v_mfma_f32_16x16x32_bf16 v[44:47], v[186:189], v[226:229], v[44:47]
	v_mfma_f32_16x16x32_bf16 v[40:43], v[194:197], v[226:229], v[40:43]
	v_mfma_f32_16x16x32_bf16 v[28:31], v[186:189], v[234:237], v[28:31]
	v_mfma_f32_16x16x32_bf16 v[24:27], v[194:197], v[234:237], v[24:27]
	v_mfma_f32_16x16x32_bf16 v[12:15], v[186:189], v[242:245], v[12:15]
	v_mfma_f32_16x16x32_bf16 v[8:11], v[194:197], v[242:245], v[8:11]
	v_mfma_f32_16x16x32_bf16 v[60:63], v[190:193], v[222:225], v[60:63]
	v_mfma_f32_16x16x32_bf16 v[56:59], v[198:201], v[222:225], v[56:59]
	v_mfma_f32_16x16x32_bf16 v[44:47], v[190:193], v[230:233], v[44:47]
	v_mfma_f32_16x16x32_bf16 v[40:43], v[198:201], v[230:233], v[40:43]
	v_mfma_f32_16x16x32_bf16 v[28:31], v[190:193], v[238:241], v[28:31]
	v_mfma_f32_16x16x32_bf16 v[24:27], v[198:201], v[238:241], v[24:27]
	v_mfma_f32_16x16x32_bf16 v[12:15], v[190:193], v[246:249], v[12:15]
	v_mfma_f32_16x16x32_bf16 v[8:11], v[198:201], v[246:249], v[8:11]
	v_mfma_f32_16x16x32_bf16 v[52:55], v[202:205], v[218:221], v[52:55]
	v_mfma_f32_16x16x32_bf16 v[48:51], v[210:213], v[218:221], v[48:51]
	v_mfma_f32_16x16x32_bf16 v[36:39], v[202:205], v[226:229], v[36:39]
	v_mfma_f32_16x16x32_bf16 v[32:35], v[210:213], v[226:229], v[32:35]
	v_mfma_f32_16x16x32_bf16 v[20:23], v[202:205], v[234:237], v[20:23]
	v_mfma_f32_16x16x32_bf16 v[16:19], v[210:213], v[234:237], v[16:19]
	v_mfma_f32_16x16x32_bf16 v[4:7], v[202:205], v[242:245], v[4:7]
	v_mfma_f32_16x16x32_bf16 v[0:3], v[210:213], v[242:245], v[0:3]
	v_mfma_f32_16x16x32_bf16 v[52:55], v[206:209], v[222:225], v[52:55]
	v_mfma_f32_16x16x32_bf16 v[48:51], v[214:217], v[222:225], v[48:51]
	v_mfma_f32_16x16x32_bf16 v[36:39], v[206:209], v[230:233], v[36:39]
	v_mfma_f32_16x16x32_bf16 v[32:35], v[214:217], v[230:233], v[32:35]
	v_mfma_f32_16x16x32_bf16 v[20:23], v[206:209], v[238:241], v[20:23]
	v_mfma_f32_16x16x32_bf16 v[16:19], v[214:217], v[238:241], v[16:19]
	v_mfma_f32_16x16x32_bf16 v[4:7], v[206:209], v[246:249], v[4:7]
	v_mfma_f32_16x16x32_bf16 v[0:3], v[214:217], v[246:249], v[0:3]
	s_setprio 0
	s_barrier
	s_add_i32 s45, s45, 2
	s_add_u32 s36, s36, 0x100
	s_addc_u32 s37, s37, 0
	s_add_u32 s43, s43, 0x100
	s_addc_u32 s44, s44, 0
	s_cmp_gt_u32 s45, 13
	s_cbranch_scc0 .LBB0_157
	s_and_b64 vcc, exec, s[24:25]
	s_cbranch_vccz .LBB0_160
	s_barrier

; #define PG8_STAGE(bufoff, gbase, voff) do { _Pragma("unroll") for (int _i = 0; _i < 2; ++_i) \
;         __builtin_amdgcn_global_load_lds((const unsigned*)((const char*)(gbase) + (voff)[_i]), (PG8_LAS unsigned*)(lds + (bufoff) + ldsw + _i * 8192), 16, 0, 0); } while (0)
; #define PG8_LDA(dst, b, h) do { _Pragma("unroll") for (int m = 0; m < 4; ++m) _Pragma("unroll") for (int k = 0; k < 2; ++k) dst[m][k] = *(const PG8_LAS bf16x8*)(lds + PG8_SA(b, h) + aoff + m * 2048 + k * 1024); } while (0)
; #define PG8_LDB(dst, b, h) do { _Pragma("unroll") for (int n = 0; n < 2; ++n) _Pragma("unroll") for (int k = 0; k < 2; ++k) dst[n][k] = *(const PG8_LAS bf16x8*)(lds + PG8_SB(b, h) + boff + n * 2048 + k * 1024); } while (0)
; #define PG8_MMA(ai, bj, At, Bt) do { __builtin_amdgcn_s_setprio(1); _Pragma("unroll") for (int m = 0; m < 4; ++m) _Pragma("unroll") for (int n = 0; n < 2; ++n) _Pragma("unroll") for (int k = 0; k < 2; ++k) \
;         acc[ai][bj][m][n] = __builtin_amdgcn_mfma_f32_16x16x32_bf16(Bt[n][k], At[m][k], acc[ai][bj][m][n], 0, 0, 0); __builtin_amdgcn_s_setprio(0); } while (0)
; #define PG8_WAIT_V(n) asm volatile("s_waitcnt vmcnt(" #n ")" ::: "memory")
; #define PG8_WAIT_L(n) asm volatile("s_waitcnt lgkmcnt(" #n ")" ::: "memory")
; #define PG8_BAR __builtin_amdgcn_s_barrier()
; #define PG8_SCHED __builtin_amdgcn_sched_barrier(0)
; template <class Epi, class Sched, bool ALIGN_EPI = false, bool SP2 = false>
; __device__ __forceinline__ void gemm_phase(PG8_LAS unsigned char* lds, const Gemm g, const Sched& S, const Epi& E) {
;     ...
;             PG8_LDB(B0, 0, 0); PG8_LDB(B1, 0, 1); PG8_SCHED; PG8_LDA(At, 0, 0); PG8_STAGE(PG8_SA(1, 1), a1 + hstepA, voffA);
;             PG8_WAIT_V(8); PG8_WAIT_L(0); PG8_BAR; PG8_MMA(0, 0, At, B0); PG8_MMA(0, 1, At, B1); PG8_BAR; PG8_SCHED;
;             PG8_LDA(At, 0, 1); PG8_STAGE(PG8_SB(0, 0), b2, voffB); PG8_STAGE(PG8_SB(0, 1), b2 + hstepB, voffB); PG8_STAGE(PG8_SA(0, 0), a2, voffA);
;             PG8_WAIT_V(8); PG8_WAIT_L(0); PG8_BAR; PG8_MMA(1, 0, At, B0); PG8_MMA(1, 1, At, B1); PG8_BAR; PG8_SCHED;
.LBB0_470:
	ds_read_b128 v[158:161], v155
	ds_read_b128 v[162:165], v155 offset:1024
	ds_read_b128 v[166:169], v155 offset:2048
	ds_read_b128 v[170:173], v155 offset:3072
	ds_read_b128 v[174:177], v156
	ds_read_b128 v[178:181], v156 offset:1024
	ds_read_b128 v[186:189], v156 offset:2048
	ds_read_b128 v[190:193], v156 offset:3072
	s_add_u32 s12, s0, 0xfffc0080
	s_addc_u32 s13, s1, -1
	s_cmp_eq_u32 s44, 4
	s_cselect_b32 s17, s38, s13
	s_cselect_b32 s16, s39, s12
	s_cselect_b32 s13, s40, s43
	s_cselect_b32 s12, s41, s42
	v_lshl_add_u64 v[182:183], s[0:1], 0, v[140:141]
	s_add_i32 m0, s22, 0xc000
	ds_read_b128 v[194:197], v157
	ds_read_b128 v[198:201], v157 offset:1024
	ds_read_b128 v[202:205], v157 offset:2048
	ds_read_b128 v[206:209], v157 offset:3072
	ds_read_b128 v[210:213], v157 offset:4096
	ds_read_b128 v[214:217], v157 offset:5120
	ds_read_b128 v[218:221], v157 offset:6144
	ds_read_b128 v[222:225], v157 offset:7168
	global_load_lds_dwordx4 v[182:183], off
	v_lshl_add_u64 v[182:183], s[0:1], 0, v[142:143]
	s_add_i32 m0, s22, 0xe000
	s_nop 0
	global_load_lds_dwordx4 v[182:183], off
	s_waitcnt vmcnt(8)
	s_waitcnt lgkmcnt(0)
	s_barrier
	s_setprio 1
	s_waitcnt lgkmcnt(0)
	v_mfma_f32_16x16x32_bf16 v[124:127], v[158:161], v[194:197], v[124:127]
	v_mfma_f32_16x16x32_bf16 v[120:123], v[166:169], v[194:197], v[120:123]
	v_mfma_f32_16x16x32_bf16 v[116:119], v[158:161], v[202:205], v[116:119]
	v_mfma_f32_16x16x32_bf16 v[112:115], v[166:169], v[202:205], v[112:115]
	v_mfma_f32_16x16x32_bf16 v[108:111], v[158:161], v[210:213], v[108:111]
	v_mfma_f32_16x16x32_bf16 v[100:103], v[166:169], v[210:213], v[100:103]
	v_mfma_f32_16x16x32_bf16 v[92:95], v[158:161], v[218:221], v[92:95]
	v_mfma_f32_16x16x32_bf16 v[84:87], v[166:169], v[218:221], v[84:87]
	v_mfma_f32_16x16x32_bf16 v[124:127], v[162:165], v[198:201], v[124:127]
	v_mfma_f32_16x16x32_bf16 v[120:123], v[170:173], v[198:201], v[120:123]
	v_mfma_f32_16x16x32_bf16 v[116:119], v[162:165], v[206:209], v[116:119]
	v_mfma_f32_16x16x32_bf16 v[112:115], v[170:173], v[206:209], v[112:115]
	v_mfma_f32_16x16x32_bf16 v[108:111], v[162:165], v[214:217], v[108:111]
	v_mfma_f32_16x16x32_bf16 v[100:103], v[170:173], v[214:217], v[100:103]
	v_mfma_f32_16x16x32_bf16 v[92:95], v[162:165], v[222:225], v[92:95]
	v_mfma_f32_16x16x32_bf16 v[84:87], v[170:173], v[222:225], v[84:87]
	v_mfma_f32_16x16x32_bf16 v[104:107], v[174:177], v[194:197], v[104:107]
	v_mfma_f32_16x16x32_bf16 v[96:99], v[186:189], v[194:197], v[96:99]
	v_mfma_f32_16x16x32_bf16 v[88:91], v[174:177], v[202:205], v[88:91]
	v_mfma_f32_16x16x32_bf16 v[80:83], v[186:189], v[202:205], v[80:83]
	v_mfma_f32_16x16x32_bf16 v[76:79], v[174:177], v[210:213], v[76:79]
	v_mfma_f32_16x16x32_bf16 v[72:75], v[186:189], v[210:213], v[72:75]
	v_mfma_f32_16x16x32_bf16 v[68:71], v[174:177], v[218:221], v[68:71]
	v_mfma_f32_16x16x32_bf16 v[64:67], v[186:189], v[218:221], v[64:67]
	v_mfma_f32_16x16x32_bf16 v[104:107], v[178:181], v[198:201], v[104:107]
	v_mfma_f32_16x16x32_bf16 v[96:99], v[190:193], v[198:201], v[96:99]
	v_mfma_f32_16x16x32_bf16 v[88:91], v[178:181], v[206:209], v[88:91]
	v_mfma_f32_16x16x32_bf16 v[80:83], v[190:193], v[206:209], v[80:83]
	v_mfma_f32_16x16x32_bf16 v[76:79], v[178:181], v[214:217], v[76:79]
	v_mfma_f32_16x16x32_bf16 v[72:75], v[190:193], v[214:217], v[72:75]
	v_mfma_f32_16x16x32_bf16 v[68:71], v[178:181], v[222:225], v[68:71]
	v_mfma_f32_16x16x32_bf16 v[64:67], v[190:193], v[222:225], v[64:67]
	s_setprio 0
	s_barrier
	s_add_i32 s45, s33, s15
	v_lshl_add_u64 v[182:183], s[12:13], 0, v[132:133]
	s_mov_b32 m0, s45
	ds_read_b128 v[194:197], v157 offset:16384
	ds_read_b128 v[198:201], v157 offset:17408
	ds_read_b128 v[202:205], v157 offset:18432
	ds_read_b128 v[206:209], v157 offset:19456
	ds_read_b128 v[210:213], v157 offset:20480
	ds_read_b128 v[214:217], v157 offset:21504
	ds_read_b128 v[218:221], v157 offset:22528
	ds_read_b128 v[222:225], v157 offset:23552
	global_load_lds_dwordx4 v[182:183], off
	s_add_i32 m0, s45, 0x2000
	s_add_u32 s46, s12, 0x80000
	v_lshl_add_u64 v[226:227], s[12:13], 0, v[128:129]
	s_addc_u32 s47, s13, 0
	s_add_i32 s45, s34, s15
	global_load_lds_dwordx4 v[226:227], off
	v_lshl_add_u64 v[228:229], s[46:47], 0, v[132:133]
	s_mov_b32 m0, s45
	v_lshl_add_u64 v[230:231], s[16:17], 0, v[130:131]
	global_load_lds_dwordx4 v[228:229], off
	v_lshl_add_u64 v[228:229], s[46:47], 0, v[128:129]
	s_add_i32 m0, s45, 0x2000
	s_nop 0
	global_load_lds_dwordx4 v[228:229], off
	v_lshl_add_u64 v[228:229], s[16:17], 0, v[134:135]
	s_mov_b32 m0, s22
	s_nop 0
	global_load_lds_dwordx4 v[228:229], off
	s_mov_b32 m0, s25
	s_nop 0
	global_load_lds_dwordx4 v[230:231], off
	s_waitcnt vmcnt(8)
	s_waitcnt lgkmcnt(0)
	s_barrier
; #define PG8_STAGE(bufoff, gbase, voff) do { _Pragma("unroll") for (int _i = 0; _i < 2; ++_i) \
;         __builtin_amdgcn_global_load_lds((const unsigned*)((const char*)(gbase) + (voff)[_i]), (PG8_LAS unsigned*)(lds + (bufoff) + ldsw + _i * 8192), 16, 0, 0); } while (0)
; #define PG8_LDA(dst, b, h) do { _Pragma("unroll") for (int m = 0; m < 4; ++m) _Pragma("unroll") for (int k = 0; k < 2; ++k) dst[m][k] = *(const PG8_LAS bf16x8*)(lds + PG8_SA(b, h) + aoff + m * 2048 + k * 1024); } while (0)
; #define PG8_LDB(dst, b, h) do { _Pragma("unroll") for (int n = 0; n < 2; ++n) _Pragma("unroll") for (int k = 0; k < 2; ++k) dst[n][k] = *(const PG8_LAS bf16x8*)(lds + PG8_SB(b, h) + boff + n * 2048 + k * 1024); } while (0)
; #define PG8_MMA(ai, bj, At, Bt) do { __builtin_amdgcn_s_setprio(1); _Pragma("unroll") for (int m = 0; m < 4; ++m) _Pragma("unroll") for (int n = 0; n < 2; ++n) _Pragma("unroll") for (int k = 0; k < 2; ++k) \
;         acc[ai][bj][m][n] = __builtin_amdgcn_mfma_f32_16x16x32_bf16(Bt[n][k], At[m][k], acc[ai][bj][m][n], 0, 0, 0); __builtin_amdgcn_s_setprio(0); } while (0)
; #define PG8_WAIT_V(n) asm volatile("s_waitcnt vmcnt(" #n ")" ::: "memory")
; #define PG8_WAIT_L(n) asm volatile("s_waitcnt lgkmcnt(" #n ")" ::: "memory")
; #define PG8_BAR __builtin_amdgcn_s_barrier()
; #define PG8_SCHED __builtin_amdgcn_sched_barrier(0)
; template <class Epi, class Sched, bool ALIGN_EPI = false, bool SP2 = false>
; __device__ __forceinline__ void gemm_phase(PG8_LAS unsigned char* lds, const Gemm g, const Sched& S, const Epi& E) {
;     ...
;             PG8_LDA(At, 0, 1); PG8_STAGE(PG8_SB(0, 0), b2, voffB); PG8_STAGE(PG8_SB(0, 1), b2 + hstepB, voffB); PG8_STAGE(PG8_SA(0, 0), a2, voffA);
;             PG8_WAIT_V(8); PG8_WAIT_L(0); PG8_BAR; PG8_MMA(1, 0, At, B0); PG8_MMA(1, 1, At, B1); PG8_BAR; PG8_SCHED;
;             PG8_LDB(B0, 1, 0); PG8_LDB(B1, 1, 1); PG8_SCHED; PG8_LDA(At, 1, 0); PG8_STAGE(PG8_SA(0, 1), a2 + hstepA, voffA);
;             PG8_WAIT_V(8); PG8_WAIT_L(0); PG8_BAR; PG8_MMA(0, 0, At, B0); PG8_MMA(0, 1, At, B1); PG8_BAR; PG8_SCHED;
	s_setprio 1
	s_waitcnt lgkmcnt(0)
	v_mfma_f32_16x16x32_bf16 v[60:63], v[158:161], v[194:197], v[60:63]
	v_mfma_f32_16x16x32_bf16 v[56:59], v[166:169], v[194:197], v[56:59]
	v_mfma_f32_16x16x32_bf16 v[52:55], v[158:161], v[202:205], v[52:55]
	v_mfma_f32_16x16x32_bf16 v[48:51], v[166:169], v[202:205], v[48:51]
	v_mfma_f32_16x16x32_bf16 v[44:47], v[158:161], v[210:213], v[44:47]
	v_mfma_f32_16x16x32_bf16 v[36:39], v[166:169], v[210:213], v[36:39]
	v_mfma_f32_16x16x32_bf16 v[28:31], v[158:161], v[218:221], v[28:31]
	v_mfma_f32_16x16x32_bf16 v[20:23], v[166:169], v[218:221], v[20:23]
	v_mfma_f32_16x16x32_bf16 v[60:63], v[162:165], v[198:201], v[60:63]
	v_mfma_f32_16x16x32_bf16 v[56:59], v[170:173], v[198:201], v[56:59]
	v_mfma_f32_16x16x32_bf16 v[52:55], v[162:165], v[206:209], v[52:55]
	v_mfma_f32_16x16x32_bf16 v[48:51], v[170:173], v[206:209], v[48:51]
	v_mfma_f32_16x16x32_bf16 v[44:47], v[162:165], v[214:217], v[44:47]
	v_mfma_f32_16x16x32_bf16 v[36:39], v[170:173], v[214:217], v[36:39]
	v_mfma_f32_16x16x32_bf16 v[28:31], v[162:165], v[222:225], v[28:31]
	v_mfma_f32_16x16x32_bf16 v[20:23], v[170:173], v[222:225], v[20:23]
	v_mfma_f32_16x16x32_bf16 v[40:43], v[174:177], v[194:197], v[40:43]
	v_mfma_f32_16x16x32_bf16 v[32:35], v[186:189], v[194:197], v[32:35]
	v_mfma_f32_16x16x32_bf16 v[24:27], v[174:177], v[202:205], v[24:27]
	v_mfma_f32_16x16x32_bf16 v[16:19], v[186:189], v[202:205], v[16:19]
	v_mfma_f32_16x16x32_bf16 v[12:15], v[174:177], v[210:213], v[12:15]
	v_mfma_f32_16x16x32_bf16 v[8:11], v[186:189], v[210:213], v[8:11]
	v_mfma_f32_16x16x32_bf16 v[4:7], v[174:177], v[218:221], v[4:7]
	v_mfma_f32_16x16x32_bf16 v[0:3], v[186:189], v[218:221], v[0:3]
	v_mfma_f32_16x16x32_bf16 v[40:43], v[178:181], v[198:201], v[40:43]
	v_mfma_f32_16x16x32_bf16 v[32:35], v[190:193], v[198:201], v[32:35]
	v_mfma_f32_16x16x32_bf16 v[24:27], v[178:181], v[206:209], v[24:27]
	v_mfma_f32_16x16x32_bf16 v[16:19], v[190:193], v[206:209], v[16:19]
	v_mfma_f32_16x16x32_bf16 v[12:15], v[178:181], v[214:217], v[12:15]
	v_mfma_f32_16x16x32_bf16 v[8:11], v[190:193], v[214:217], v[8:11]
	v_mfma_f32_16x16x32_bf16 v[4:7], v[178:181], v[222:225], v[4:7]
	v_mfma_f32_16x16x32_bf16 v[0:3], v[190:193], v[222:225], v[0:3]
	s_setprio 0
	s_barrier
	s_add_i32 s45, 0, 0x18000
	v_add_u32_e32 v136, s45, v150
	s_add_i32 s46, 0, 0x1c000
	ds_read_b128 v[158:161], v136
	ds_read_b128 v[162:165], v136 offset:1024
	ds_read_b128 v[166:169], v136 offset:2048
	ds_read_b128 v[170:173], v136 offset:3072
	v_add_u32_e32 v136, s46, v150
	ds_read_b128 v[174:177], v136
	ds_read_b128 v[178:181], v136 offset:1024
	ds_read_b128 v[186:189], v136 offset:2048
	ds_read_b128 v[190:193], v136 offset:3072
	s_add_u32 s16, s16, 0x40000
	s_addc_u32 s17, s17, 0
	s_mov_b32 m0, s26
	v_lshl_add_u64 v[232:233], s[16:17], 0, v[134:135]
	ds_read_b128 v[194:197], v157 offset:32768
	ds_read_b128 v[198:201], v157 offset:33792
	ds_read_b128 v[202:205], v157 offset:34816
	ds_read_b128 v[206:209], v157 offset:35840
	ds_read_b128 v[210:213], v157 offset:36864
	ds_read_b128 v[214:217], v157 offset:37888
	ds_read_b128 v[218:221], v157 offset:38912
	ds_read_b128 v[222:225], v157 offset:39936
	global_load_lds_dwordx4 v[232:233], off
	v_lshl_add_u64 v[232:233], s[16:17], 0, v[130:131]
	s_mov_b32 m0, s27
	s_nop 0
	global_load_lds_dwordx4 v[232:233], off
	s_waitcnt vmcnt(8)
	s_waitcnt lgkmcnt(0)
	s_barrier
	s_setprio 1
	s_waitcnt lgkmcnt(0)
	v_mfma_f32_16x16x32_bf16 v[124:127], v[158:161], v[194:197], v[124:127]
	v_mfma_f32_16x16x32_bf16 v[120:123], v[166:169], v[194:197], v[120:123]
	v_mfma_f32_16x16x32_bf16 v[116:119], v[158:161], v[202:205], v[116:119]
	v_mfma_f32_16x16x32_bf16 v[112:115], v[166:169], v[202:205], v[112:115]
	v_mfma_f32_16x16x32_bf16 v[108:111], v[158:161], v[210:213], v[108:111]
	v_mfma_f32_16x16x32_bf16 v[100:103], v[166:169], v[210:213], v[100:103]
	v_mfma_f32_16x16x32_bf16 v[92:95], v[158:161], v[218:221], v[92:95]
	v_mfma_f32_16x16x32_bf16 v[84:87], v[166:169], v[218:221], v[84:87]
	v_mfma_f32_16x16x32_bf16 v[124:127], v[162:165], v[198:201], v[124:127]
	v_mfma_f32_16x16x32_bf16 v[120:123], v[170:173], v[198:201], v[120:123]
	v_mfma_f32_16x16x32_bf16 v[116:119], v[162:165], v[206:209], v[116:119]
	v_mfma_f32_16x16x32_bf16 v[112:115], v[170:173], v[206:209], v[112:115]
	v_mfma_f32_16x16x32_bf16 v[108:111], v[162:165], v[214:217], v[108:111]
	v_mfma_f32_16x16x32_bf16 v[100:103], v[170:173], v[214:217], v[100:103]
	v_mfma_f32_16x16x32_bf16 v[92:95], v[162:165], v[222:225], v[92:95]
	v_mfma_f32_16x16x32_bf16 v[84:87], v[170:173], v[222:225], v[84:87]
	v_mfma_f32_16x16x32_bf16 v[104:107], v[174:177], v[194:197], v[104:107]
	v_mfma_f32_16x16x32_bf16 v[96:99], v[186:189], v[194:197], v[96:99]
	v_mfma_f32_16x16x32_bf16 v[88:91], v[174:177], v[202:205], v[88:91]
	v_mfma_f32_16x16x32_bf16 v[80:83], v[186:189], v[202:205], v[80:83]
	v_mfma_f32_16x16x32_bf16 v[76:79], v[174:177], v[210:213], v[76:79]
	v_mfma_f32_16x16x32_bf16 v[72:75], v[186:189], v[210:213], v[72:75]
	v_mfma_f32_16x16x32_bf16 v[68:71], v[174:177], v[218:221], v[68:71]
	v_mfma_f32_16x16x32_bf16 v[64:67], v[186:189], v[218:221], v[64:67]
	v_mfma_f32_16x16x32_bf16 v[104:107], v[178:181], v[198:201], v[104:107]
	v_mfma_f32_16x16x32_bf16 v[96:99], v[190:193], v[198:201], v[96:99]
	v_mfma_f32_16x16x32_bf16 v[88:91], v[178:181], v[206:209], v[88:91]
	v_mfma_f32_16x16x32_bf16 v[80:83], v[190:193], v[206:209], v[80:83]
	v_mfma_f32_16x16x32_bf16 v[76:79], v[178:181], v[214:217], v[76:79]
	v_mfma_f32_16x16x32_bf16 v[72:75], v[190:193], v[214:217], v[72:75]
	v_mfma_f32_16x16x32_bf16 v[68:71], v[178:181], v[222:225], v[68:71]
	v_mfma_f32_16x16x32_bf16 v[64:67], v[190:193], v[222:225], v[64:67]
	s_setprio 0
	s_barrier
; #define PG8_STAGE(bufoff, gbase, voff) do { _Pragma("unroll") for (int _i = 0; _i < 2; ++_i) \
;         __builtin_amdgcn_global_load_lds((const unsigned*)((const char*)(gbase) + (voff)[_i]), (PG8_LAS unsigned*)(lds + (bufoff) + ldsw + _i * 8192), 16, 0, 0); } while (0)
; #define PG8_LDA(dst, b, h) do { _Pragma("unroll") for (int m = 0; m < 4; ++m) _Pragma("unroll") for (int k = 0; k < 2; ++k) dst[m][k] = *(const PG8_LAS bf16x8*)(lds + PG8_SA(b, h) + aoff + m * 2048 + k * 1024); } while (0)
; #define PG8_LDB(dst, b, h) do { _Pragma("unroll") for (int n = 0; n < 2; ++n) _Pragma("unroll") for (int k = 0; k < 2; ++k) dst[n][k] = *(const PG8_LAS bf16x8*)(lds + PG8_SB(b, h) + boff + n * 2048 + k * 1024); } while (0)
; #define PG8_WAIT_V(n) asm volatile("s_waitcnt vmcnt(" #n ")" ::: "memory")
; #define PG8_WAIT_L(n) asm volatile("s_waitcnt lgkmcnt(" #n ")" ::: "memory")
; #define PG8_BAR __builtin_amdgcn_s_barrier()
; #define PG8_SCHED __builtin_amdgcn_sched_barrier(0)
; template <class Epi, class Sched, bool ALIGN_EPI = false, bool SP2 = false>
; __device__ __forceinline__ void gemm_phase(PG8_LAS unsigned char* lds, const Gemm g, const Sched& S, const Epi& E) {
;     ...
;             PG8_LDB(B0, 1, 0); PG8_LDB(B1, 1, 1); PG8_SCHED; PG8_LDA(At, 1, 0); PG8_STAGE(PG8_SA(0, 1), a2 + hstepA, voffA);
;             PG8_WAIT_V(8); PG8_WAIT_L(0); PG8_BAR; PG8_MMA(0, 0, At, B0); PG8_MMA(0, 1, At, B1); PG8_BAR; PG8_SCHED;
;             PG8_LDA(At, 1, 1); PG8_STAGE(PG8_SB(1, 0), b3, voffB); PG8_STAGE(PG8_SB(1, 1), b3 + hstepB, voffB); PG8_STAGE(PG8_SA(1, 0), a3, voffA);
;             PG8_WAIT_V(8); PG8_WAIT_L(0); PG8_BAR; PG8_MMA(1, 0, At, B0); PG8_MMA(1, 1, At, B1); PG8_BAR; PG8_SCHED;
;     __device__ __forceinline__ void operator()(const f32x4 (&acc)[2][2][4][2], const pg8::Unit& u, int wr, int wc, int fr, int fq) const {
;         float* base = part + (size_t)(u.koff >> 10) * 8192 * 256;
; #pragma unroll
;         for (int ai = 0; ai < 2; ++ai)
; #pragma unroll
;             for (int m = 0; m < 4; ++m) {
;                 const int row = u.pm * 256 + ai * 128 + wr * 64 + m * 16 + fr;
; #pragma unroll
;                 for (int bj = 0; bj < 2; ++bj) {
;                     float* p = base + (size_t)row * 256 + 128 * bj + 32 * wc + 8 * fq;
;                     *(f32x4*)p = acc[ai][bj][m][0]; *(f32x4*)(p + 4) = acc[ai][bj][m][1];
;                 }
;             }
	s_add_i32 s16, s45, s15
	v_lshl_add_u64 v[182:183], v[182:183], 0, s[10:11]
	s_mov_b32 m0, s16
	ds_read_b128 v[194:197], v157 offset:49152
	ds_read_b128 v[198:201], v157 offset:50176
	ds_read_b128 v[202:205], v157 offset:51200
	ds_read_b128 v[206:209], v157 offset:52224
	ds_read_b128 v[210:213], v157 offset:53248
	ds_read_b128 v[214:217], v157 offset:54272
	ds_read_b128 v[218:221], v157 offset:55296
	ds_read_b128 v[222:225], v157 offset:56320
	global_load_lds_dwordx4 v[182:183], off
	s_add_i32 m0, s16, 0x2000
	s_add_u32 s12, s12, 0x80080
	v_lshl_add_u64 v[182:183], v[226:227], 0, s[10:11]
	s_addc_u32 s13, s13, 0
	s_add_i32 s16, s46, s15
	global_load_lds_dwordx4 v[182:183], off
	v_lshl_add_u64 v[182:183], s[12:13], 0, v[132:133]
	s_mov_b32 m0, s16
	s_nop 0
	global_load_lds_dwordx4 v[182:183], off
	v_lshl_add_u64 v[182:183], s[12:13], 0, v[128:129]
	s_add_i32 m0, s16, 0x2000
	s_nop 0
	global_load_lds_dwordx4 v[182:183], off
	v_lshl_add_u64 v[182:183], v[228:229], 0, s[10:11]
	s_mov_b32 m0, s30
	s_nop 0
	global_load_lds_dwordx4 v[182:183], off
	v_lshl_add_u64 v[182:183], v[230:231], 0, s[10:11]
	s_mov_b32 m0, s31
	s_nop 0
	global_load_lds_dwordx4 v[182:183], off
	s_waitcnt vmcnt(8)
	s_waitcnt lgkmcnt(0)
	s_barrier
	s_setprio 1
	s_waitcnt lgkmcnt(0)
	v_mfma_f32_16x16x32_bf16 v[60:63], v[158:161], v[194:197], v[60:63]
	v_mfma_f32_16x16x32_bf16 v[56:59], v[166:169], v[194:197], v[56:59]
	v_mfma_f32_16x16x32_bf16 v[52:55], v[158:161], v[202:205], v[52:55]
	v_mfma_f32_16x16x32_bf16 v[48:51], v[166:169], v[202:205], v[48:51]
	v_mfma_f32_16x16x32_bf16 v[44:47], v[158:161], v[210:213], v[44:47]
	v_mfma_f32_16x16x32_bf16 v[36:39], v[166:169], v[210:213], v[36:39]
	v_mfma_f32_16x16x32_bf16 v[28:31], v[158:161], v[218:221], v[28:31]
	v_mfma_f32_16x16x32_bf16 v[20:23], v[166:169], v[218:221], v[20:23]
	v_mfma_f32_16x16x32_bf16 v[60:63], v[162:165], v[198:201], v[60:63]
	v_mfma_f32_16x16x32_bf16 v[56:59], v[170:173], v[198:201], v[56:59]
	v_mfma_f32_16x16x32_bf16 v[52:55], v[162:165], v[206:209], v[52:55]
	v_mfma_f32_16x16x32_bf16 v[48:51], v[170:173], v[206:209], v[48:51]
	v_mfma_f32_16x16x32_bf16 v[44:47], v[162:165], v[214:217], v[44:47]
	v_mfma_f32_16x16x32_bf16 v[36:39], v[170:173], v[214:217], v[36:39]
	v_mfma_f32_16x16x32_bf16 v[28:31], v[162:165], v[222:225], v[28:31]
	v_mfma_f32_16x16x32_bf16 v[20:23], v[170:173], v[222:225], v[20:23]
	v_mfma_f32_16x16x32_bf16 v[40:43], v[174:177], v[194:197], v[40:43]
	v_mfma_f32_16x16x32_bf16 v[32:35], v[186:189], v[194:197], v[32:35]
	v_mfma_f32_16x16x32_bf16 v[24:27], v[174:177], v[202:205], v[24:27]
	v_mfma_f32_16x16x32_bf16 v[16:19], v[186:189], v[202:205], v[16:19]
	v_mfma_f32_16x16x32_bf16 v[12:15], v[174:177], v[210:213], v[12:15]
	v_mfma_f32_16x16x32_bf16 v[8:11], v[186:189], v[210:213], v[8:11]
	v_mfma_f32_16x16x32_bf16 v[4:7], v[174:177], v[218:221], v[4:7]
	v_mfma_f32_16x16x32_bf16 v[0:3], v[186:189], v[218:221], v[0:3]
	v_mfma_f32_16x16x32_bf16 v[40:43], v[178:181], v[198:201], v[40:43]
	v_mfma_f32_16x16x32_bf16 v[32:35], v[190:193], v[198:201], v[32:35]
	v_mfma_f32_16x16x32_bf16 v[24:27], v[178:181], v[206:209], v[24:27]
	v_mfma_f32_16x16x32_bf16 v[16:19], v[190:193], v[206:209], v[16:19]
	v_mfma_f32_16x16x32_bf16 v[12:15], v[178:181], v[214:217], v[12:15]
	v_mfma_f32_16x16x32_bf16 v[8:11], v[190:193], v[214:217], v[8:11]
	v_mfma_f32_16x16x32_bf16 v[4:7], v[178:181], v[222:225], v[4:7]
	v_mfma_f32_16x16x32_bf16 v[0:3], v[190:193], v[222:225], v[0:3]
	s_setprio 0
	s_barrier
	s_add_i32 s44, s44, 2
	s_add_u32 s0, s0, 0x100
	s_addc_u32 s1, s1, 0
	s_add_u32 s42, s42, 0x100
	s_addc_u32 s43, s43, 0
	s_cmp_gt_u32 s44, 5
	s_cbranch_scc0 .LBB0_470
	s_ashr_i32 s0, s24, 10
	s_ashr_i32 s1, s0, 31
	s_lshl_b64 s[0:1], s[0:1], 23
	v_lshl_add_u64 v[158:159], v[138:139], 0, s[0:1]
	s_lshl_b32 s0, s23, 8
	v_add_u32_e32 v136, s0, v148
	v_lshlrev_b64 v[160:161], 10, v[136:137]
	v_lshl_add_u64 v[160:161], v[158:159], 0, v[160:161]
	global_store_dwordx4 v[160:161], v[124:127], off
	global_store_dwordx4 v[160:161], v[120:123], off offset:16
	global_store_dwordx4 v[160:161], v[104:107], off offset:512
	global_store_dwordx4 v[160:161], v[96:99], off offset:528
	s_and_b64 vcc, exec, vcc
	s_mov_b32 s24, s35
	v_add_u32_e32 v96, s0, v152
	v_mov_b32_e32 v97, v137
	v_lshlrev_b64 v[96:97], 10, v[96:97]
	v_lshl_add_u64 v[96:97], v[158:159], 0, v[96:97]
	global_store_dwordx4 v[96:97], v[116:119], off
	global_store_dwordx4 v[96:97], v[112:115], off offset:16
	global_store_dwordx4 v[96:97], v[88:91], off offset:512
	global_store_dwordx4 v[96:97], v[80:83], off offset:528
	s_mov_b32 s23, s37
	s_nop 0
	v_add_u32_e32 v80, s0, v153
	v_mov_b32_e32 v81, v137
	v_lshlrev_b64 v[80:81], 10, v[80:81]
	v_lshl_add_u64 v[80:81], v[158:159], 0, v[80:81]
	global_store_dwordx4 v[80:81], v[108:111], off
	global_store_dwordx4 v[80:81], v[100:103], off offset:16
	global_store_dwordx4 v[80:81], v[76:79], off offset:512
	global_store_dwordx4 v[80:81], v[72:75], off offset:528
	s_nop 1
	v_add_u32_e32 v72, s0, v154
	v_mov_b32_e32 v73, v137
	v_lshlrev_b64 v[72:73], 10, v[72:73]
	v_lshl_add_u64 v[72:73], v[158:159], 0, v[72:73]
	global_store_dwordx4 v[72:73], v[92:95], off
	global_store_dwordx4 v[72:73], v[84:87], off offset:16
	global_store_dwordx4 v[72:73], v[68:71], off offset:512
	global_store_dwordx4 v[72:73], v[64:67], off offset:528
	s_nop 1
	v_add_u32_e32 v64, 0x80, v136
	v_mov_b32_e32 v65, v137
	v_lshlrev_b64 v[64:65], 10, v[64:65]
	v_lshl_add_u64 v[64:65], v[158:159], 0, v[64:65]
	global_store_dwordx4 v[64:65], v[60:63], off
	global_store_dwordx4 v[64:65], v[56:59], off offset:16
	global_store_dwordx4 v[64:65], v[40:43], off offset:512
	global_store_dwordx4 v[64:65], v[32:35], off offset:528
	s_nop 1
	v_add_u32_e32 v32, 0x90, v136
	v_mov_b32_e32 v33, v137
	v_lshlrev_b64 v[32:33], 10, v[32:33]
	v_lshl_add_u64 v[32:33], v[158:159], 0, v[32:33]
	global_store_dwordx4 v[32:33], v[52:55], off
	global_store_dwordx4 v[32:33], v[48:51], off offset:16
	global_store_dwordx4 v[32:33], v[24:27], off offset:512
	global_store_dwordx4 v[32:33], v[16:19], off offset:528
	s_nop 1
	v_add_u32_e32 v16, 0xa0, v136
	v_mov_b32_e32 v17, v137
	v_lshlrev_b64 v[16:17], 10, v[16:17]
	v_lshl_add_u64 v[16:17], v[158:159], 0, v[16:17]
	v_add_u32_e32 v136, 0xb0, v136
	global_store_dwordx4 v[16:17], v[44:47], off
	global_store_dwordx4 v[16:17], v[36:39], off offset:16
	global_store_dwordx4 v[16:17], v[12:15], off offset:512
	global_store_dwordx4 v[16:17], v[8:11], off offset:528
	s_nop 1
	v_lshlrev_b64 v[8:9], 10, v[136:137]
	v_lshl_add_u64 v[8:9], v[158:159], 0, v[8:9]
	global_store_dwordx4 v[8:9], v[28:31], off
	global_store_dwordx4 v[8:9], v[20:23], off offset:16
	global_store_dwordx4 v[8:9], v[4:7], off offset:512
	global_store_dwordx4 v[8:9], v[0:3], off offset:528
	s_cbranch_vccz .LBB0_469
	s_waitcnt vmcnt(0)
	s_cmpk_gt_u32 s14, 0xff
	s_cbranch_scc1 .LBB0_474
	s_barrier

; #define PG8_STAGE(bufoff, gbase, voff) do { _Pragma("unroll") for (int _i = 0; _i < 2; ++_i) \
;         __builtin_amdgcn_global_load_lds((const unsigned*)((const char*)(gbase) + (voff)[_i]), (PG8_LAS unsigned*)(lds + (bufoff) + ldsw + _i * 8192), 16, 0, 0); } while (0)
; #define PG8_LDA(dst, b, h) do { _Pragma("unroll") for (int m = 0; m < 4; ++m) _Pragma("unroll") for (int k = 0; k < 2; ++k) dst[m][k] = *(const PG8_LAS bf16x8*)(lds + PG8_SA(b, h) + aoff + m * 2048 + k * 1024); } while (0)
; #define PG8_LDB(dst, b, h) do { _Pragma("unroll") for (int n = 0; n < 2; ++n) _Pragma("unroll") for (int k = 0; k < 2; ++k) dst[n][k] = *(const PG8_LAS bf16x8*)(lds + PG8_SB(b, h) + boff + n * 2048 + k * 1024); } while (0)
; #define PG8_MMA(ai, bj, At, Bt) do { __builtin_amdgcn_s_setprio(1); _Pragma("unroll") for (int m = 0; m < 4; ++m) _Pragma("unroll") for (int n = 0; n < 2; ++n) _Pragma("unroll") for (int k = 0; k < 2; ++k) \
;         acc[ai][bj][m][n] = __builtin_amdgcn_mfma_f32_16x16x32_bf16(Bt[n][k], At[m][k], acc[ai][bj][m][n], 0, 0, 0); __builtin_amdgcn_s_setprio(0); } while (0)
; #define PG8_WAIT_V(n) asm volatile("s_waitcnt vmcnt(" #n ")" ::: "memory")
; #define PG8_WAIT_L(n) asm volatile("s_waitcnt lgkmcnt(" #n ")" ::: "memory")
; #define PG8_BAR __builtin_amdgcn_s_barrier()
; #define PG8_SCHED __builtin_amdgcn_sched_barrier(0)
; template <class Epi, class Sched, bool ALIGN_EPI = false, bool SP2 = false>
; __device__ __forceinline__ void gemm_phase(PG8_LAS unsigned char* lds, const Gemm g, const Sched& S, const Epi& E) {
;     ...
;             PG8_LDB(B0, 0, 0); PG8_LDB(B1, 0, 1); PG8_SCHED; PG8_LDA(At, 0, 0); PG8_STAGE(PG8_SA(1, 1), a1 + hstepA, voffA);
;             PG8_WAIT_V(8); PG8_WAIT_L(0); PG8_BAR; PG8_MMA(0, 0, At, B0); PG8_MMA(0, 1, At, B1); PG8_BAR; PG8_SCHED;
;             PG8_LDA(At, 0, 1); PG8_STAGE(PG8_SB(0, 0), b2, voffB); PG8_STAGE(PG8_SB(0, 1), b2 + hstepB, voffB); PG8_STAGE(PG8_SA(0, 0), a2, voffA);
;             PG8_WAIT_V(8); PG8_WAIT_L(0); PG8_BAR; PG8_MMA(1, 0, At, B0); PG8_MMA(1, 1, At, B1); PG8_BAR; PG8_SCHED;
.LBB0_935:
	ds_read_b128 v[120:123], v237
	ds_read_b128 v[124:127], v237 offset:1024
	ds_read_b128 v[136:139], v237 offset:2048
	ds_read_b128 v[140:143], v237 offset:3072
	ds_read_b128 v[144:147], v238
	ds_read_b128 v[148:151], v238 offset:1024
	ds_read_b128 v[152:155], v238 offset:2048
	ds_read_b128 v[156:159], v238 offset:3072
	s_add_u32 s38, s36, 0xfffc0080
	s_addc_u32 s39, s37, -1
	s_cmp_eq_u32 s58, 12
	s_cselect_b32 s41, s9, s39
	s_cselect_b32 s40, s27, s38
	s_cselect_b32 s39, s25, s57
	s_cselect_b32 s38, s35, s56
	v_lshl_add_u64 v[214:215], s[36:37], 0, v[198:199]
	s_add_i32 m0, s44, 0xc000
	ds_read_b128 v[160:163], v239
	ds_read_b128 v[164:167], v239 offset:1024
	ds_read_b128 v[168:171], v239 offset:2048
	ds_read_b128 v[172:175], v239 offset:3072
	ds_read_b128 v[176:179], v239 offset:4096
	ds_read_b128 v[180:183], v239 offset:5120
	ds_read_b128 v[206:209], v239 offset:6144
	ds_read_b128 v[210:213], v239 offset:7168
	global_load_lds_dwordx4 v[214:215], off
	v_lshl_add_u64 v[214:215], s[36:37], 0, v[200:201]
	s_add_i32 m0, s44, 0xe000
	s_nop 0
	global_load_lds_dwordx4 v[214:215], off
	s_waitcnt vmcnt(8)
	s_waitcnt lgkmcnt(0)
	s_barrier
	s_setprio 1
	s_waitcnt lgkmcnt(0)
	v_mfma_f32_16x16x32_bf16 v[132:135], v[120:123], v[160:163], v[132:135]
	v_mfma_f32_16x16x32_bf16 v[128:131], v[136:139], v[160:163], v[128:131]
	v_mfma_f32_16x16x32_bf16 v[108:111], v[120:123], v[168:171], v[108:111]
	v_mfma_f32_16x16x32_bf16 v[104:107], v[136:139], v[168:171], v[104:107]
	v_mfma_f32_16x16x32_bf16 v[92:95], v[120:123], v[176:179], v[92:95]
	v_mfma_f32_16x16x32_bf16 v[88:91], v[136:139], v[176:179], v[88:91]
	v_mfma_f32_16x16x32_bf16 v[76:79], v[120:123], v[206:209], v[76:79]
	v_mfma_f32_16x16x32_bf16 v[72:75], v[136:139], v[206:209], v[72:75]
	v_mfma_f32_16x16x32_bf16 v[132:135], v[124:127], v[164:167], v[132:135]
	v_mfma_f32_16x16x32_bf16 v[128:131], v[140:143], v[164:167], v[128:131]
	v_mfma_f32_16x16x32_bf16 v[108:111], v[124:127], v[172:175], v[108:111]
	v_mfma_f32_16x16x32_bf16 v[104:107], v[140:143], v[172:175], v[104:107]
	v_mfma_f32_16x16x32_bf16 v[92:95], v[124:127], v[180:183], v[92:95]
	v_mfma_f32_16x16x32_bf16 v[88:91], v[140:143], v[180:183], v[88:91]
	v_mfma_f32_16x16x32_bf16 v[76:79], v[124:127], v[210:213], v[76:79]
	v_mfma_f32_16x16x32_bf16 v[72:75], v[140:143], v[210:213], v[72:75]
	v_mfma_f32_16x16x32_bf16 v[116:119], v[144:147], v[160:163], v[116:119]
	v_mfma_f32_16x16x32_bf16 v[112:115], v[152:155], v[160:163], v[112:115]
	v_mfma_f32_16x16x32_bf16 v[100:103], v[144:147], v[168:171], v[100:103]
	v_mfma_f32_16x16x32_bf16 v[96:99], v[152:155], v[168:171], v[96:99]
	v_mfma_f32_16x16x32_bf16 v[84:87], v[144:147], v[176:179], v[84:87]
	v_mfma_f32_16x16x32_bf16 v[80:83], v[152:155], v[176:179], v[80:83]
	v_mfma_f32_16x16x32_bf16 v[68:71], v[144:147], v[206:209], v[68:71]
	v_mfma_f32_16x16x32_bf16 v[64:67], v[152:155], v[206:209], v[64:67]
	v_mfma_f32_16x16x32_bf16 v[116:119], v[148:151], v[164:167], v[116:119]
	v_mfma_f32_16x16x32_bf16 v[112:115], v[156:159], v[164:167], v[112:115]
	v_mfma_f32_16x16x32_bf16 v[100:103], v[148:151], v[172:175], v[100:103]
	v_mfma_f32_16x16x32_bf16 v[96:99], v[156:159], v[172:175], v[96:99]
	v_mfma_f32_16x16x32_bf16 v[84:87], v[148:151], v[180:183], v[84:87]
	v_mfma_f32_16x16x32_bf16 v[80:83], v[156:159], v[180:183], v[80:83]
	v_mfma_f32_16x16x32_bf16 v[68:71], v[148:151], v[210:213], v[68:71]
	v_mfma_f32_16x16x32_bf16 v[64:67], v[156:159], v[210:213], v[64:67]
	s_setprio 0
	s_barrier
	s_add_i32 s59, s53, s43
	v_lshl_add_u64 v[214:215], s[38:39], 0, v[188:189]
	s_mov_b32 m0, s59
	ds_read_b128 v[160:163], v239 offset:16384
	ds_read_b128 v[164:167], v239 offset:17408
	ds_read_b128 v[168:171], v239 offset:18432
	ds_read_b128 v[172:175], v239 offset:19456
	ds_read_b128 v[176:179], v239 offset:20480
	ds_read_b128 v[180:183], v239 offset:21504
	ds_read_b128 v[206:209], v239 offset:22528
	ds_read_b128 v[210:213], v239 offset:23552
	global_load_lds_dwordx4 v[214:215], off
	s_add_i32 m0, s59, 0x2000
	s_add_u32 s60, s38, 0x40000
	v_lshl_add_u64 v[216:217], s[38:39], 0, v[192:193]
	s_addc_u32 s61, s39, 0
	s_add_i32 s59, s54, s43
	global_load_lds_dwordx4 v[216:217], off
	v_lshl_add_u64 v[218:219], s[60:61], 0, v[188:189]
	s_mov_b32 m0, s59
	v_lshl_add_u64 v[220:221], s[40:41], 0, v[190:191]
	global_load_lds_dwordx4 v[218:219], off
	v_lshl_add_u64 v[218:219], s[60:61], 0, v[192:193]
	s_add_i32 m0, s59, 0x2000
	s_nop 0
	global_load_lds_dwordx4 v[218:219], off
	v_lshl_add_u64 v[218:219], s[40:41], 0, v[186:187]
	s_mov_b32 m0, s44
	s_nop 0
	global_load_lds_dwordx4 v[218:219], off
	s_mov_b32 m0, s45
	s_nop 0
	global_load_lds_dwordx4 v[220:221], off
	s_waitcnt vmcnt(8)
	s_waitcnt lgkmcnt(0)
	s_barrier
; #define PG8_STAGE(bufoff, gbase, voff) do { _Pragma("unroll") for (int _i = 0; _i < 2; ++_i) \
;         __builtin_amdgcn_global_load_lds((const unsigned*)((const char*)(gbase) + (voff)[_i]), (PG8_LAS unsigned*)(lds + (bufoff) + ldsw + _i * 8192), 16, 0, 0); } while (0)
; #define PG8_LDA(dst, b, h) do { _Pragma("unroll") for (int m = 0; m < 4; ++m) _Pragma("unroll") for (int k = 0; k < 2; ++k) dst[m][k] = *(const PG8_LAS bf16x8*)(lds + PG8_SA(b, h) + aoff + m * 2048 + k * 1024); } while (0)
; #define PG8_LDB(dst, b, h) do { _Pragma("unroll") for (int n = 0; n < 2; ++n) _Pragma("unroll") for (int k = 0; k < 2; ++k) dst[n][k] = *(const PG8_LAS bf16x8*)(lds + PG8_SB(b, h) + boff + n * 2048 + k * 1024); } while (0)
; #define PG8_MMA(ai, bj, At, Bt) do { __builtin_amdgcn_s_setprio(1); _Pragma("unroll") for (int m = 0; m < 4; ++m) _Pragma("unroll") for (int n = 0; n < 2; ++n) _Pragma("unroll") for (int k = 0; k < 2; ++k) \
;         acc[ai][bj][m][n] = __builtin_amdgcn_mfma_f32_16x16x32_bf16(Bt[n][k], At[m][k], acc[ai][bj][m][n], 0, 0, 0); __builtin_amdgcn_s_setprio(0); } while (0)
; #define PG8_WAIT_V(n) asm volatile("s_waitcnt vmcnt(" #n ")" ::: "memory")
; #define PG8_WAIT_L(n) asm volatile("s_waitcnt lgkmcnt(" #n ")" ::: "memory")
; #define PG8_BAR __builtin_amdgcn_s_barrier()
; #define PG8_SCHED __builtin_amdgcn_sched_barrier(0)
; template <class Epi, class Sched, bool ALIGN_EPI = false, bool SP2 = false>
; __device__ __forceinline__ void gemm_phase(PG8_LAS unsigned char* lds, const Gemm g, const Sched& S, const Epi& E) {
;     ...
;             PG8_LDA(At, 0, 1); PG8_STAGE(PG8_SB(0, 0), b2, voffB); PG8_STAGE(PG8_SB(0, 1), b2 + hstepB, voffB); PG8_STAGE(PG8_SA(0, 0), a2, voffA);
;             PG8_WAIT_V(8); PG8_WAIT_L(0); PG8_BAR; PG8_MMA(1, 0, At, B0); PG8_MMA(1, 1, At, B1); PG8_BAR; PG8_SCHED;
;             PG8_LDB(B0, 1, 0); PG8_LDB(B1, 1, 1); PG8_SCHED; PG8_LDA(At, 1, 0); PG8_STAGE(PG8_SA(0, 1), a2 + hstepA, voffA);
;             PG8_WAIT_V(8); PG8_WAIT_L(0); PG8_BAR; PG8_MMA(0, 0, At, B0); PG8_MMA(0, 1, At, B1); PG8_BAR; PG8_SCHED;
	s_setprio 1
	s_waitcnt lgkmcnt(0)
	v_mfma_f32_16x16x32_bf16 v[60:63], v[120:123], v[160:163], v[60:63]
	v_mfma_f32_16x16x32_bf16 v[56:59], v[136:139], v[160:163], v[56:59]
	v_mfma_f32_16x16x32_bf16 v[44:47], v[120:123], v[168:171], v[44:47]
	v_mfma_f32_16x16x32_bf16 v[40:43], v[136:139], v[168:171], v[40:43]
	v_mfma_f32_16x16x32_bf16 v[28:31], v[120:123], v[176:179], v[28:31]
	v_mfma_f32_16x16x32_bf16 v[24:27], v[136:139], v[176:179], v[24:27]
	v_mfma_f32_16x16x32_bf16 v[12:15], v[120:123], v[206:209], v[12:15]
	v_mfma_f32_16x16x32_bf16 v[8:11], v[136:139], v[206:209], v[8:11]
	v_mfma_f32_16x16x32_bf16 v[60:63], v[124:127], v[164:167], v[60:63]
	v_mfma_f32_16x16x32_bf16 v[56:59], v[140:143], v[164:167], v[56:59]
	v_mfma_f32_16x16x32_bf16 v[44:47], v[124:127], v[172:175], v[44:47]
	v_mfma_f32_16x16x32_bf16 v[40:43], v[140:143], v[172:175], v[40:43]
	v_mfma_f32_16x16x32_bf16 v[28:31], v[124:127], v[180:183], v[28:31]
	v_mfma_f32_16x16x32_bf16 v[24:27], v[140:143], v[180:183], v[24:27]
	v_mfma_f32_16x16x32_bf16 v[12:15], v[124:127], v[210:213], v[12:15]
	v_mfma_f32_16x16x32_bf16 v[8:11], v[140:143], v[210:213], v[8:11]
	v_mfma_f32_16x16x32_bf16 v[52:55], v[144:147], v[160:163], v[52:55]
	v_mfma_f32_16x16x32_bf16 v[48:51], v[152:155], v[160:163], v[48:51]
	v_mfma_f32_16x16x32_bf16 v[36:39], v[144:147], v[168:171], v[36:39]
	v_mfma_f32_16x16x32_bf16 v[32:35], v[152:155], v[168:171], v[32:35]
	v_mfma_f32_16x16x32_bf16 v[20:23], v[144:147], v[176:179], v[20:23]
	v_mfma_f32_16x16x32_bf16 v[16:19], v[152:155], v[176:179], v[16:19]
	v_mfma_f32_16x16x32_bf16 v[4:7], v[144:147], v[206:209], v[4:7]
	v_mfma_f32_16x16x32_bf16 v[0:3], v[152:155], v[206:209], v[0:3]
	v_mfma_f32_16x16x32_bf16 v[52:55], v[148:151], v[164:167], v[52:55]
	v_mfma_f32_16x16x32_bf16 v[48:51], v[156:159], v[164:167], v[48:51]
	v_mfma_f32_16x16x32_bf16 v[36:39], v[148:151], v[172:175], v[36:39]
	v_mfma_f32_16x16x32_bf16 v[32:35], v[156:159], v[172:175], v[32:35]
	v_mfma_f32_16x16x32_bf16 v[20:23], v[148:151], v[180:183], v[20:23]
	v_mfma_f32_16x16x32_bf16 v[16:19], v[156:159], v[180:183], v[16:19]
	v_mfma_f32_16x16x32_bf16 v[4:7], v[148:151], v[210:213], v[4:7]
	v_mfma_f32_16x16x32_bf16 v[0:3], v[156:159], v[210:213], v[0:3]
	s_setprio 0
	s_barrier
	s_add_i32 s59, 0, 0x18000
	s_add_i32 s60, 0, 0x1c000
	v_add_u32_e32 v140, s59, v234
	v_add_u32_e32 v156, s60, v234
	ds_read_b128 v[120:123], v140
	ds_read_b128 v[124:127], v140 offset:1024
	ds_read_b128 v[136:139], v140 offset:2048
	ds_read_b128 v[140:143], v140 offset:3072
	ds_read_b128 v[144:147], v156
	ds_read_b128 v[148:151], v156 offset:1024
	ds_read_b128 v[152:155], v156 offset:2048
	ds_read_b128 v[156:159], v156 offset:3072
	s_add_u32 s40, s40, 0x40000
	s_addc_u32 s41, s41, 0
	s_mov_b32 m0, s46
	v_lshl_add_u64 v[222:223], s[40:41], 0, v[186:187]
	ds_read_b128 v[160:163], v239 offset:32768
	ds_read_b128 v[164:167], v239 offset:33792
	ds_read_b128 v[168:171], v239 offset:34816
	ds_read_b128 v[172:175], v239 offset:35840
	ds_read_b128 v[176:179], v239 offset:36864
	ds_read_b128 v[180:183], v239 offset:37888
	ds_read_b128 v[206:209], v239 offset:38912
	ds_read_b128 v[210:213], v239 offset:39936
	global_load_lds_dwordx4 v[222:223], off
	v_lshl_add_u64 v[222:223], s[40:41], 0, v[190:191]
	s_mov_b32 m0, s47
	s_nop 0
	global_load_lds_dwordx4 v[222:223], off
	s_waitcnt vmcnt(8)
	s_waitcnt lgkmcnt(0)
	s_barrier
	s_setprio 1
	s_waitcnt lgkmcnt(0)
	v_mfma_f32_16x16x32_bf16 v[132:135], v[120:123], v[160:163], v[132:135]
	v_mfma_f32_16x16x32_bf16 v[128:131], v[136:139], v[160:163], v[128:131]
	v_mfma_f32_16x16x32_bf16 v[108:111], v[120:123], v[168:171], v[108:111]
	v_mfma_f32_16x16x32_bf16 v[104:107], v[136:139], v[168:171], v[104:107]
	v_mfma_f32_16x16x32_bf16 v[92:95], v[120:123], v[176:179], v[92:95]
	v_mfma_f32_16x16x32_bf16 v[88:91], v[136:139], v[176:179], v[88:91]
	v_mfma_f32_16x16x32_bf16 v[76:79], v[120:123], v[206:209], v[76:79]
	v_mfma_f32_16x16x32_bf16 v[72:75], v[136:139], v[206:209], v[72:75]
	v_mfma_f32_16x16x32_bf16 v[132:135], v[124:127], v[164:167], v[132:135]
	v_mfma_f32_16x16x32_bf16 v[128:131], v[140:143], v[164:167], v[128:131]
	v_mfma_f32_16x16x32_bf16 v[108:111], v[124:127], v[172:175], v[108:111]
	v_mfma_f32_16x16x32_bf16 v[104:107], v[140:143], v[172:175], v[104:107]
	v_mfma_f32_16x16x32_bf16 v[92:95], v[124:127], v[180:183], v[92:95]
	v_mfma_f32_16x16x32_bf16 v[88:91], v[140:143], v[180:183], v[88:91]
	v_mfma_f32_16x16x32_bf16 v[76:79], v[124:127], v[210:213], v[76:79]
	v_mfma_f32_16x16x32_bf16 v[72:75], v[140:143], v[210:213], v[72:75]
	v_mfma_f32_16x16x32_bf16 v[116:119], v[144:147], v[160:163], v[116:119]
	v_mfma_f32_16x16x32_bf16 v[112:115], v[152:155], v[160:163], v[112:115]
	v_mfma_f32_16x16x32_bf16 v[100:103], v[144:147], v[168:171], v[100:103]
	v_mfma_f32_16x16x32_bf16 v[96:99], v[152:155], v[168:171], v[96:99]
	v_mfma_f32_16x16x32_bf16 v[84:87], v[144:147], v[176:179], v[84:87]
	v_mfma_f32_16x16x32_bf16 v[80:83], v[152:155], v[176:179], v[80:83]
	v_mfma_f32_16x16x32_bf16 v[68:71], v[144:147], v[206:209], v[68:71]
	v_mfma_f32_16x16x32_bf16 v[64:67], v[152:155], v[206:209], v[64:67]
	v_mfma_f32_16x16x32_bf16 v[116:119], v[148:151], v[164:167], v[116:119]
	v_mfma_f32_16x16x32_bf16 v[112:115], v[156:159], v[164:167], v[112:115]
	v_mfma_f32_16x16x32_bf16 v[100:103], v[148:151], v[172:175], v[100:103]
	v_mfma_f32_16x16x32_bf16 v[96:99], v[156:159], v[172:175], v[96:99]
	v_mfma_f32_16x16x32_bf16 v[84:87], v[148:151], v[180:183], v[84:87]
	v_mfma_f32_16x16x32_bf16 v[80:83], v[156:159], v[180:183], v[80:83]
	v_mfma_f32_16x16x32_bf16 v[68:71], v[148:151], v[210:213], v[68:71]
	v_mfma_f32_16x16x32_bf16 v[64:67], v[156:159], v[210:213], v[64:67]
	s_setprio 0
	s_barrier
; #define PG8_STAGE(bufoff, gbase, voff) do { _Pragma("unroll") for (int _i = 0; _i < 2; ++_i) \
;         __builtin_amdgcn_global_load_lds((const unsigned*)((const char*)(gbase) + (voff)[_i]), (PG8_LAS unsigned*)(lds + (bufoff) + ldsw + _i * 8192), 16, 0, 0); } while (0)
; #define PG8_LDA(dst, b, h) do { _Pragma("unroll") for (int m = 0; m < 4; ++m) _Pragma("unroll") for (int k = 0; k < 2; ++k) dst[m][k] = *(const PG8_LAS bf16x8*)(lds + PG8_SA(b, h) + aoff + m * 2048 + k * 1024); } while (0)
; #define PG8_LDB(dst, b, h) do { _Pragma("unroll") for (int n = 0; n < 2; ++n) _Pragma("unroll") for (int k = 0; k < 2; ++k) dst[n][k] = *(const PG8_LAS bf16x8*)(lds + PG8_SB(b, h) + boff + n * 2048 + k * 1024); } while (0)
; #define PG8_MMA(ai, bj, At, Bt) do { __builtin_amdgcn_s_setprio(1); _Pragma("unroll") for (int m = 0; m < 4; ++m) _Pragma("unroll") for (int n = 0; n < 2; ++n) _Pragma("unroll") for (int k = 0; k < 2; ++k) \
;         acc[ai][bj][m][n] = __builtin_amdgcn_mfma_f32_16x16x32_bf16(Bt[n][k], At[m][k], acc[ai][bj][m][n], 0, 0, 0); __builtin_amdgcn_s_setprio(0); } while (0)
; #define PG8_WAIT_V(n) asm volatile("s_waitcnt vmcnt(" #n ")" ::: "memory")
; #define PG8_WAIT_L(n) asm volatile("s_waitcnt lgkmcnt(" #n ")" ::: "memory")
; #define PG8_BAR __builtin_amdgcn_s_barrier()
; #define PG8_SCHED __builtin_amdgcn_sched_barrier(0)
; template <class Epi, class Sched, bool ALIGN_EPI = false, bool SP2 = false>
; __device__ __forceinline__ void gemm_phase(PG8_LAS unsigned char* lds, const Gemm g, const Sched& S, const Epi& E) {
;     ...
;         for (int t = 0; t < nt; t += 2) {
;     ...
;             PG8_LDB(B0, 1, 0); PG8_LDB(B1, 1, 1); PG8_SCHED; PG8_LDA(At, 1, 0); PG8_STAGE(PG8_SA(0, 1), a2 + hstepA, voffA);
;             PG8_WAIT_V(8); PG8_WAIT_L(0); PG8_BAR; PG8_MMA(0, 0, At, B0); PG8_MMA(0, 1, At, B1); PG8_BAR; PG8_SCHED;
;             PG8_LDA(At, 1, 1); PG8_STAGE(PG8_SB(1, 0), b3, voffB); PG8_STAGE(PG8_SB(1, 1), b3 + hstepB, voffB); PG8_STAGE(PG8_SA(1, 0), a3, voffA);
;             PG8_WAIT_V(8); PG8_WAIT_L(0); PG8_BAR; PG8_MMA(1, 0, At, B0); PG8_MMA(1, 1, At, B1); PG8_BAR; PG8_SCHED;
	s_add_i32 s40, s59, s43
	v_lshl_add_u64 v[214:215], v[214:215], 0, s[20:21]
	s_mov_b32 m0, s40
	ds_read_b128 v[160:163], v239 offset:49152
	ds_read_b128 v[164:167], v239 offset:50176
	ds_read_b128 v[168:171], v239 offset:51200
	ds_read_b128 v[172:175], v239 offset:52224
	ds_read_b128 v[176:179], v239 offset:53248
	ds_read_b128 v[180:183], v239 offset:54272
	ds_read_b128 v[206:209], v239 offset:55296
	ds_read_b128 v[210:213], v239 offset:56320
	global_load_lds_dwordx4 v[214:215], off
	s_add_i32 m0, s40, 0x2000
	s_add_u32 s38, s38, 0x40080
	v_lshl_add_u64 v[214:215], v[216:217], 0, s[20:21]
	s_addc_u32 s39, s39, 0
	s_add_i32 s40, s60, s43
	global_load_lds_dwordx4 v[214:215], off
	v_lshl_add_u64 v[214:215], s[38:39], 0, v[188:189]
	s_mov_b32 m0, s40
	s_nop 0
	global_load_lds_dwordx4 v[214:215], off
	v_lshl_add_u64 v[214:215], s[38:39], 0, v[192:193]
	s_add_i32 m0, s40, 0x2000
	s_nop 0
	global_load_lds_dwordx4 v[214:215], off
	v_lshl_add_u64 v[214:215], v[218:219], 0, s[20:21]
	s_mov_b32 m0, s48
	s_nop 0
	global_load_lds_dwordx4 v[214:215], off
	v_lshl_add_u64 v[214:215], v[220:221], 0, s[20:21]
	s_mov_b32 m0, s49
	s_nop 0
	global_load_lds_dwordx4 v[214:215], off
	s_waitcnt vmcnt(8)
	s_waitcnt lgkmcnt(0)
	s_barrier
	s_setprio 1
	s_waitcnt lgkmcnt(0)
	v_mfma_f32_16x16x32_bf16 v[60:63], v[120:123], v[160:163], v[60:63]
	v_mfma_f32_16x16x32_bf16 v[56:59], v[136:139], v[160:163], v[56:59]
	v_mfma_f32_16x16x32_bf16 v[44:47], v[120:123], v[168:171], v[44:47]
	v_mfma_f32_16x16x32_bf16 v[40:43], v[136:139], v[168:171], v[40:43]
	v_mfma_f32_16x16x32_bf16 v[28:31], v[120:123], v[176:179], v[28:31]
	v_mfma_f32_16x16x32_bf16 v[24:27], v[136:139], v[176:179], v[24:27]
	v_mfma_f32_16x16x32_bf16 v[12:15], v[120:123], v[206:209], v[12:15]
	v_mfma_f32_16x16x32_bf16 v[8:11], v[136:139], v[206:209], v[8:11]
	v_mfma_f32_16x16x32_bf16 v[60:63], v[124:127], v[164:167], v[60:63]
	v_mfma_f32_16x16x32_bf16 v[56:59], v[140:143], v[164:167], v[56:59]
	v_mfma_f32_16x16x32_bf16 v[44:47], v[124:127], v[172:175], v[44:47]
	v_mfma_f32_16x16x32_bf16 v[40:43], v[140:143], v[172:175], v[40:43]
	v_mfma_f32_16x16x32_bf16 v[28:31], v[124:127], v[180:183], v[28:31]
	v_mfma_f32_16x16x32_bf16 v[24:27], v[140:143], v[180:183], v[24:27]
	v_mfma_f32_16x16x32_bf16 v[12:15], v[124:127], v[210:213], v[12:15]
	v_mfma_f32_16x16x32_bf16 v[8:11], v[140:143], v[210:213], v[8:11]
	v_mfma_f32_16x16x32_bf16 v[52:55], v[144:147], v[160:163], v[52:55]
	v_mfma_f32_16x16x32_bf16 v[48:51], v[152:155], v[160:163], v[48:51]
	v_mfma_f32_16x16x32_bf16 v[36:39], v[144:147], v[168:171], v[36:39]
	v_mfma_f32_16x16x32_bf16 v[32:35], v[152:155], v[168:171], v[32:35]
	v_mfma_f32_16x16x32_bf16 v[20:23], v[144:147], v[176:179], v[20:23]
	v_mfma_f32_16x16x32_bf16 v[16:19], v[152:155], v[176:179], v[16:19]
	v_mfma_f32_16x16x32_bf16 v[4:7], v[144:147], v[206:209], v[4:7]
	v_mfma_f32_16x16x32_bf16 v[0:3], v[152:155], v[206:209], v[0:3]
	v_mfma_f32_16x16x32_bf16 v[52:55], v[148:151], v[164:167], v[52:55]
	v_mfma_f32_16x16x32_bf16 v[48:51], v[156:159], v[164:167], v[48:51]
	v_mfma_f32_16x16x32_bf16 v[36:39], v[148:151], v[172:175], v[36:39]
	v_mfma_f32_16x16x32_bf16 v[32:35], v[156:159], v[172:175], v[32:35]
	v_mfma_f32_16x16x32_bf16 v[20:23], v[148:151], v[180:183], v[20:23]
	v_mfma_f32_16x16x32_bf16 v[16:19], v[156:159], v[180:183], v[16:19]
	v_mfma_f32_16x16x32_bf16 v[4:7], v[148:151], v[210:213], v[4:7]
	v_mfma_f32_16x16x32_bf16 v[0:3], v[156:159], v[210:213], v[0:3]
	s_setprio 0
	s_barrier
	s_add_i32 s58, s58, 2
	s_add_u32 s36, s36, 0x100
	s_addc_u32 s37, s37, 0
	s_add_u32 s56, s56, 0x100
	s_addc_u32 s57, s57, 0
	s_cmp_gt_u32 s58, 13
	s_cbranch_scc0 .LBB0_935
	s_and_b64 vcc, exec, s[22:23]
	s_cbranch_vccz .LBB0_938
	s_barrier

; #define PG8_STAGE(bufoff, gbase, voff) do { _Pragma("unroll") for (int _i = 0; _i < 2; ++_i) \
;         __builtin_amdgcn_global_load_lds((const unsigned*)((const char*)(gbase) + (voff)[_i]), (PG8_LAS unsigned*)(lds + (bufoff) + ldsw + _i * 8192), 16, 0, 0); } while (0)
; #define PG8_LDA(dst, b, h) do { _Pragma("unroll") for (int m = 0; m < 4; ++m) _Pragma("unroll") for (int k = 0; k < 2; ++k) dst[m][k] = *(const PG8_LAS bf16x8*)(lds + PG8_SA(b, h) + aoff + m * 2048 + k * 1024); } while (0)
; #define PG8_LDB(dst, b, h) do { _Pragma("unroll") for (int n = 0; n < 2; ++n) _Pragma("unroll") for (int k = 0; k < 2; ++k) dst[n][k] = *(const PG8_LAS bf16x8*)(lds + PG8_SB(b, h) + boff + n * 2048 + k * 1024); } while (0)
; #define PG8_MMA(ai, bj, At, Bt) do { __builtin_amdgcn_s_setprio(1); _Pragma("unroll") for (int m = 0; m < 4; ++m) _Pragma("unroll") for (int n = 0; n < 2; ++n) _Pragma("unroll") for (int k = 0; k < 2; ++k) \
;         acc[ai][bj][m][n] = __builtin_amdgcn_mfma_f32_16x16x32_bf16(Bt[n][k], At[m][k], acc[ai][bj][m][n], 0, 0, 0); __builtin_amdgcn_s_setprio(0); } while (0)
; #define PG8_WAIT_V(n) asm volatile("s_waitcnt vmcnt(" #n ")" ::: "memory")
; #define PG8_WAIT_L(n) asm volatile("s_waitcnt lgkmcnt(" #n ")" ::: "memory")
; #define PG8_BAR __builtin_amdgcn_s_barrier()
; #define PG8_SCHED __builtin_amdgcn_sched_barrier(0)
; template <class Epi, class Sched, bool ALIGN_EPI = false, bool SP2 = false>
; __device__ __forceinline__ void gemm_phase(PG8_LAS unsigned char* lds, const Gemm g, const Sched& S, const Epi& E) {
;     ...
;             PG8_LDB(B0, 0, 0); PG8_LDB(B1, 0, 1); PG8_SCHED; PG8_LDA(At, 0, 0); PG8_STAGE(PG8_SA(1, 1), a1 + hstepA, voffA);
;             PG8_WAIT_V(8); PG8_WAIT_L(0); PG8_BAR; PG8_MMA(0, 0, At, B0); PG8_MMA(0, 1, At, B1); PG8_BAR; PG8_SCHED;
;             PG8_LDA(At, 0, 1); PG8_STAGE(PG8_SB(0, 0), b2, voffB); PG8_STAGE(PG8_SB(0, 1), b2 + hstepB, voffB); PG8_STAGE(PG8_SA(0, 0), a2, voffA);
;             PG8_WAIT_V(8); PG8_WAIT_L(0); PG8_BAR; PG8_MMA(1, 0, At, B0); PG8_MMA(1, 1, At, B1); PG8_BAR; PG8_SCHED;
.LBB0_1007:
	ds_read_b128 v[128:131], v176
	ds_read_b128 v[132:135], v176 offset:1024
	ds_read_b128 v[136:139], v176 offset:2048
	ds_read_b128 v[140:143], v176 offset:3072
	ds_read_b128 v[162:165], v177
	ds_read_b128 v[166:169], v177 offset:1024
	ds_read_b128 v[170:173], v177 offset:2048
	ds_read_b128 v[180:183], v177 offset:3072
	s_add_u32 s36, s34, 0xfffc0080
	s_addc_u32 s37, s35, -1
	s_cmp_eq_u32 s56, 12
	s_cselect_b32 s39, s25, s37
	s_cselect_b32 s38, s52, s36
	s_cselect_b32 s37, s23, s55
	s_cselect_b32 s36, s53, s54
	v_lshl_add_u64 v[218:219], s[34:35], 0, v[154:155]
	s_add_i32 m0, s41, 0xc000
	ds_read_b128 v[186:189], v178
	ds_read_b128 v[190:193], v178 offset:1024
	ds_read_b128 v[194:197], v178 offset:2048
	ds_read_b128 v[198:201], v178 offset:3072
	ds_read_b128 v[202:205], v178 offset:4096
	ds_read_b128 v[206:209], v178 offset:5120
	ds_read_b128 v[210:213], v178 offset:6144
	ds_read_b128 v[214:217], v178 offset:7168
	global_load_lds_dwordx4 v[218:219], off
	v_lshl_add_u64 v[218:219], s[34:35], 0, v[156:157]
	s_add_i32 m0, s41, 0xe000
	s_nop 0
	global_load_lds_dwordx4 v[218:219], off
	s_waitcnt vmcnt(8)
	s_waitcnt lgkmcnt(0)
	s_barrier
	s_setprio 1
	s_waitcnt lgkmcnt(0)
	v_mfma_f32_16x16x32_bf16 v[124:127], v[128:131], v[186:189], v[124:127]
	v_mfma_f32_16x16x32_bf16 v[120:123], v[136:139], v[186:189], v[120:123]
	v_mfma_f32_16x16x32_bf16 v[108:111], v[128:131], v[194:197], v[108:111]
	v_mfma_f32_16x16x32_bf16 v[104:107], v[136:139], v[194:197], v[104:107]
	v_mfma_f32_16x16x32_bf16 v[92:95], v[128:131], v[202:205], v[92:95]
	v_mfma_f32_16x16x32_bf16 v[88:91], v[136:139], v[202:205], v[88:91]
	v_mfma_f32_16x16x32_bf16 v[76:79], v[128:131], v[210:213], v[76:79]
	v_mfma_f32_16x16x32_bf16 v[72:75], v[136:139], v[210:213], v[72:75]
	v_mfma_f32_16x16x32_bf16 v[124:127], v[132:135], v[190:193], v[124:127]
	v_mfma_f32_16x16x32_bf16 v[120:123], v[140:143], v[190:193], v[120:123]
	v_mfma_f32_16x16x32_bf16 v[108:111], v[132:135], v[198:201], v[108:111]
	v_mfma_f32_16x16x32_bf16 v[104:107], v[140:143], v[198:201], v[104:107]
	v_mfma_f32_16x16x32_bf16 v[92:95], v[132:135], v[206:209], v[92:95]
	v_mfma_f32_16x16x32_bf16 v[88:91], v[140:143], v[206:209], v[88:91]
	v_mfma_f32_16x16x32_bf16 v[76:79], v[132:135], v[214:217], v[76:79]
	v_mfma_f32_16x16x32_bf16 v[72:75], v[140:143], v[214:217], v[72:75]
	v_mfma_f32_16x16x32_bf16 v[116:119], v[162:165], v[186:189], v[116:119]
	v_mfma_f32_16x16x32_bf16 v[112:115], v[170:173], v[186:189], v[112:115]
	v_mfma_f32_16x16x32_bf16 v[100:103], v[162:165], v[194:197], v[100:103]
	v_mfma_f32_16x16x32_bf16 v[96:99], v[170:173], v[194:197], v[96:99]
	v_mfma_f32_16x16x32_bf16 v[84:87], v[162:165], v[202:205], v[84:87]
	v_mfma_f32_16x16x32_bf16 v[80:83], v[170:173], v[202:205], v[80:83]
	v_mfma_f32_16x16x32_bf16 v[68:71], v[162:165], v[210:213], v[68:71]
	v_mfma_f32_16x16x32_bf16 v[64:67], v[170:173], v[210:213], v[64:67]
	v_mfma_f32_16x16x32_bf16 v[116:119], v[166:169], v[190:193], v[116:119]
	v_mfma_f32_16x16x32_bf16 v[112:115], v[180:183], v[190:193], v[112:115]
	v_mfma_f32_16x16x32_bf16 v[100:103], v[166:169], v[198:201], v[100:103]
	v_mfma_f32_16x16x32_bf16 v[96:99], v[180:183], v[198:201], v[96:99]
	v_mfma_f32_16x16x32_bf16 v[84:87], v[166:169], v[206:209], v[84:87]
	v_mfma_f32_16x16x32_bf16 v[80:83], v[180:183], v[206:209], v[80:83]
	v_mfma_f32_16x16x32_bf16 v[68:71], v[166:169], v[214:217], v[68:71]
	v_mfma_f32_16x16x32_bf16 v[64:67], v[180:183], v[214:217], v[64:67]
	s_setprio 0
	s_barrier
	s_add_i32 s57, s48, s40
	v_lshl_add_u64 v[218:219], s[36:37], 0, v[146:147]
	s_mov_b32 m0, s57
	ds_read_b128 v[186:189], v178 offset:16384
	ds_read_b128 v[190:193], v178 offset:17408
	ds_read_b128 v[194:197], v178 offset:18432
	ds_read_b128 v[198:201], v178 offset:19456
	ds_read_b128 v[202:205], v178 offset:20480
	ds_read_b128 v[206:209], v178 offset:21504
	ds_read_b128 v[210:213], v178 offset:22528
	ds_read_b128 v[214:217], v178 offset:23552
	global_load_lds_dwordx4 v[218:219], off
	s_add_i32 m0, s57, 0x2000
	s_add_u32 s58, s36, 0x40000
	v_lshl_add_u64 v[220:221], s[36:37], 0, v[150:151]
	s_addc_u32 s59, s37, 0
	s_add_i32 s57, s49, s40
	global_load_lds_dwordx4 v[220:221], off
	v_lshl_add_u64 v[222:223], s[58:59], 0, v[146:147]
	s_mov_b32 m0, s57
	v_lshl_add_u64 v[224:225], s[38:39], 0, v[148:149]
	global_load_lds_dwordx4 v[222:223], off
	v_lshl_add_u64 v[222:223], s[58:59], 0, v[150:151]
	s_add_i32 m0, s57, 0x2000
	s_nop 0
	global_load_lds_dwordx4 v[222:223], off
	v_lshl_add_u64 v[222:223], s[38:39], 0, v[144:145]
	s_mov_b32 m0, s41
	s_nop 0
	global_load_lds_dwordx4 v[222:223], off
	s_mov_b32 m0, s42
	s_nop 0
	global_load_lds_dwordx4 v[224:225], off
	s_waitcnt vmcnt(8)
	s_waitcnt lgkmcnt(0)
	s_barrier
; #define PG8_STAGE(bufoff, gbase, voff) do { _Pragma("unroll") for (int _i = 0; _i < 2; ++_i) \
;         __builtin_amdgcn_global_load_lds((const unsigned*)((const char*)(gbase) + (voff)[_i]), (PG8_LAS unsigned*)(lds + (bufoff) + ldsw + _i * 8192), 16, 0, 0); } while (0)
; #define PG8_LDA(dst, b, h) do { _Pragma("unroll") for (int m = 0; m < 4; ++m) _Pragma("unroll") for (int k = 0; k < 2; ++k) dst[m][k] = *(const PG8_LAS bf16x8*)(lds + PG8_SA(b, h) + aoff + m * 2048 + k * 1024); } while (0)
; #define PG8_LDB(dst, b, h) do { _Pragma("unroll") for (int n = 0; n < 2; ++n) _Pragma("unroll") for (int k = 0; k < 2; ++k) dst[n][k] = *(const PG8_LAS bf16x8*)(lds + PG8_SB(b, h) + boff + n * 2048 + k * 1024); } while (0)
; #define PG8_MMA(ai, bj, At, Bt) do { __builtin_amdgcn_s_setprio(1); _Pragma("unroll") for (int m = 0; m < 4; ++m) _Pragma("unroll") for (int n = 0; n < 2; ++n) _Pragma("unroll") for (int k = 0; k < 2; ++k) \
;         acc[ai][bj][m][n] = __builtin_amdgcn_mfma_f32_16x16x32_bf16(Bt[n][k], At[m][k], acc[ai][bj][m][n], 0, 0, 0); __builtin_amdgcn_s_setprio(0); } while (0)
; #define PG8_WAIT_V(n) asm volatile("s_waitcnt vmcnt(" #n ")" ::: "memory")
; #define PG8_WAIT_L(n) asm volatile("s_waitcnt lgkmcnt(" #n ")" ::: "memory")
; #define PG8_BAR __builtin_amdgcn_s_barrier()
; #define PG8_SCHED __builtin_amdgcn_sched_barrier(0)
; template <class Epi, class Sched, bool ALIGN_EPI = false, bool SP2 = false>
; __device__ __forceinline__ void gemm_phase(PG8_LAS unsigned char* lds, const Gemm g, const Sched& S, const Epi& E) {
;     ...
;             PG8_LDA(At, 0, 1); PG8_STAGE(PG8_SB(0, 0), b2, voffB); PG8_STAGE(PG8_SB(0, 1), b2 + hstepB, voffB); PG8_STAGE(PG8_SA(0, 0), a2, voffA);
;             PG8_WAIT_V(8); PG8_WAIT_L(0); PG8_BAR; PG8_MMA(1, 0, At, B0); PG8_MMA(1, 1, At, B1); PG8_BAR; PG8_SCHED;
;             PG8_LDB(B0, 1, 0); PG8_LDB(B1, 1, 1); PG8_SCHED; PG8_LDA(At, 1, 0); PG8_STAGE(PG8_SA(0, 1), a2 + hstepA, voffA);
;             PG8_WAIT_V(8); PG8_WAIT_L(0); PG8_BAR; PG8_MMA(0, 0, At, B0); PG8_MMA(0, 1, At, B1); PG8_BAR; PG8_SCHED;
	s_setprio 1
	s_waitcnt lgkmcnt(0)
	v_mfma_f32_16x16x32_bf16 v[60:63], v[128:131], v[186:189], v[60:63]
	v_mfma_f32_16x16x32_bf16 v[56:59], v[136:139], v[186:189], v[56:59]
	v_mfma_f32_16x16x32_bf16 v[44:47], v[128:131], v[194:197], v[44:47]
	v_mfma_f32_16x16x32_bf16 v[40:43], v[136:139], v[194:197], v[40:43]
	v_mfma_f32_16x16x32_bf16 v[28:31], v[128:131], v[202:205], v[28:31]
	v_mfma_f32_16x16x32_bf16 v[24:27], v[136:139], v[202:205], v[24:27]
	v_mfma_f32_16x16x32_bf16 v[12:15], v[128:131], v[210:213], v[12:15]
	v_mfma_f32_16x16x32_bf16 v[8:11], v[136:139], v[210:213], v[8:11]
	v_mfma_f32_16x16x32_bf16 v[60:63], v[132:135], v[190:193], v[60:63]
	v_mfma_f32_16x16x32_bf16 v[56:59], v[140:143], v[190:193], v[56:59]
	v_mfma_f32_16x16x32_bf16 v[44:47], v[132:135], v[198:201], v[44:47]
	v_mfma_f32_16x16x32_bf16 v[40:43], v[140:143], v[198:201], v[40:43]
	v_mfma_f32_16x16x32_bf16 v[28:31], v[132:135], v[206:209], v[28:31]
	v_mfma_f32_16x16x32_bf16 v[24:27], v[140:143], v[206:209], v[24:27]
	v_mfma_f32_16x16x32_bf16 v[12:15], v[132:135], v[214:217], v[12:15]
	v_mfma_f32_16x16x32_bf16 v[8:11], v[140:143], v[214:217], v[8:11]
	v_mfma_f32_16x16x32_bf16 v[52:55], v[162:165], v[186:189], v[52:55]
	v_mfma_f32_16x16x32_bf16 v[48:51], v[170:173], v[186:189], v[48:51]
	v_mfma_f32_16x16x32_bf16 v[36:39], v[162:165], v[194:197], v[36:39]
	v_mfma_f32_16x16x32_bf16 v[32:35], v[170:173], v[194:197], v[32:35]
	v_mfma_f32_16x16x32_bf16 v[20:23], v[162:165], v[202:205], v[20:23]
	v_mfma_f32_16x16x32_bf16 v[16:19], v[170:173], v[202:205], v[16:19]
	v_mfma_f32_16x16x32_bf16 v[4:7], v[162:165], v[210:213], v[4:7]
	v_mfma_f32_16x16x32_bf16 v[0:3], v[170:173], v[210:213], v[0:3]
	v_mfma_f32_16x16x32_bf16 v[52:55], v[166:169], v[190:193], v[52:55]
	v_mfma_f32_16x16x32_bf16 v[48:51], v[180:183], v[190:193], v[48:51]
	v_mfma_f32_16x16x32_bf16 v[36:39], v[166:169], v[198:201], v[36:39]
	v_mfma_f32_16x16x32_bf16 v[32:35], v[180:183], v[198:201], v[32:35]
	v_mfma_f32_16x16x32_bf16 v[20:23], v[166:169], v[206:209], v[20:23]
	v_mfma_f32_16x16x32_bf16 v[16:19], v[180:183], v[206:209], v[16:19]
	v_mfma_f32_16x16x32_bf16 v[4:7], v[166:169], v[214:217], v[4:7]
	v_mfma_f32_16x16x32_bf16 v[0:3], v[180:183], v[214:217], v[0:3]
	s_setprio 0
	s_barrier
	s_add_i32 s57, 0, 0x18000
	s_add_i32 s58, 0, 0x1c000
	v_add_u32_e32 v140, s57, v175
	v_add_u32_e32 v179, s58, v175
	ds_read_b128 v[128:131], v140
	ds_read_b128 v[132:135], v140 offset:1024
	ds_read_b128 v[136:139], v140 offset:2048
	ds_read_b128 v[140:143], v140 offset:3072
	ds_read_b128 v[162:165], v179
	ds_read_b128 v[166:169], v179 offset:1024
	ds_read_b128 v[170:173], v179 offset:2048
	ds_read_b128 v[180:183], v179 offset:3072
	s_add_u32 s38, s38, 0x40000
	s_addc_u32 s39, s39, 0
	s_mov_b32 m0, s43
	v_lshl_add_u64 v[226:227], s[38:39], 0, v[144:145]
	ds_read_b128 v[186:189], v178 offset:32768
	ds_read_b128 v[190:193], v178 offset:33792
	ds_read_b128 v[194:197], v178 offset:34816
	ds_read_b128 v[198:201], v178 offset:35840
	ds_read_b128 v[202:205], v178 offset:36864
	ds_read_b128 v[206:209], v178 offset:37888
	ds_read_b128 v[210:213], v178 offset:38912
	ds_read_b128 v[214:217], v178 offset:39936
	global_load_lds_dwordx4 v[226:227], off
	v_lshl_add_u64 v[226:227], s[38:39], 0, v[148:149]
	s_mov_b32 m0, s44
	s_nop 0
	global_load_lds_dwordx4 v[226:227], off
	s_waitcnt vmcnt(8)
	s_waitcnt lgkmcnt(0)
	s_barrier
	s_setprio 1
	s_waitcnt lgkmcnt(0)
	v_mfma_f32_16x16x32_bf16 v[124:127], v[128:131], v[186:189], v[124:127]
	v_mfma_f32_16x16x32_bf16 v[120:123], v[136:139], v[186:189], v[120:123]
	v_mfma_f32_16x16x32_bf16 v[108:111], v[128:131], v[194:197], v[108:111]
	v_mfma_f32_16x16x32_bf16 v[104:107], v[136:139], v[194:197], v[104:107]
	v_mfma_f32_16x16x32_bf16 v[92:95], v[128:131], v[202:205], v[92:95]
	v_mfma_f32_16x16x32_bf16 v[88:91], v[136:139], v[202:205], v[88:91]
	v_mfma_f32_16x16x32_bf16 v[76:79], v[128:131], v[210:213], v[76:79]
	v_mfma_f32_16x16x32_bf16 v[72:75], v[136:139], v[210:213], v[72:75]
	v_mfma_f32_16x16x32_bf16 v[124:127], v[132:135], v[190:193], v[124:127]
	v_mfma_f32_16x16x32_bf16 v[120:123], v[140:143], v[190:193], v[120:123]
	v_mfma_f32_16x16x32_bf16 v[108:111], v[132:135], v[198:201], v[108:111]
	v_mfma_f32_16x16x32_bf16 v[104:107], v[140:143], v[198:201], v[104:107]
	v_mfma_f32_16x16x32_bf16 v[92:95], v[132:135], v[206:209], v[92:95]
	v_mfma_f32_16x16x32_bf16 v[88:91], v[140:143], v[206:209], v[88:91]
	v_mfma_f32_16x16x32_bf16 v[76:79], v[132:135], v[214:217], v[76:79]
	v_mfma_f32_16x16x32_bf16 v[72:75], v[140:143], v[214:217], v[72:75]
	v_mfma_f32_16x16x32_bf16 v[116:119], v[162:165], v[186:189], v[116:119]
	v_mfma_f32_16x16x32_bf16 v[112:115], v[170:173], v[186:189], v[112:115]
	v_mfma_f32_16x16x32_bf16 v[100:103], v[162:165], v[194:197], v[100:103]
	v_mfma_f32_16x16x32_bf16 v[96:99], v[170:173], v[194:197], v[96:99]
	v_mfma_f32_16x16x32_bf16 v[84:87], v[162:165], v[202:205], v[84:87]
	v_mfma_f32_16x16x32_bf16 v[80:83], v[170:173], v[202:205], v[80:83]
	v_mfma_f32_16x16x32_bf16 v[68:71], v[162:165], v[210:213], v[68:71]
	v_mfma_f32_16x16x32_bf16 v[64:67], v[170:173], v[210:213], v[64:67]
	v_mfma_f32_16x16x32_bf16 v[116:119], v[166:169], v[190:193], v[116:119]
	v_mfma_f32_16x16x32_bf16 v[112:115], v[180:183], v[190:193], v[112:115]
	v_mfma_f32_16x16x32_bf16 v[100:103], v[166:169], v[198:201], v[100:103]
	v_mfma_f32_16x16x32_bf16 v[96:99], v[180:183], v[198:201], v[96:99]
	v_mfma_f32_16x16x32_bf16 v[84:87], v[166:169], v[206:209], v[84:87]
	v_mfma_f32_16x16x32_bf16 v[80:83], v[180:183], v[206:209], v[80:83]
	v_mfma_f32_16x16x32_bf16 v[68:71], v[166:169], v[214:217], v[68:71]
	v_mfma_f32_16x16x32_bf16 v[64:67], v[180:183], v[214:217], v[64:67]
	s_setprio 0
	s_barrier
; #define PG8_STAGE(bufoff, gbase, voff) do { _Pragma("unroll") for (int _i = 0; _i < 2; ++_i) \
;         __builtin_amdgcn_global_load_lds((const unsigned*)((const char*)(gbase) + (voff)[_i]), (PG8_LAS unsigned*)(lds + (bufoff) + ldsw + _i * 8192), 16, 0, 0); } while (0)
; #define PG8_LDA(dst, b, h) do { _Pragma("unroll") for (int m = 0; m < 4; ++m) _Pragma("unroll") for (int k = 0; k < 2; ++k) dst[m][k] = *(const PG8_LAS bf16x8*)(lds + PG8_SA(b, h) + aoff + m * 2048 + k * 1024); } while (0)
; #define PG8_LDB(dst, b, h) do { _Pragma("unroll") for (int n = 0; n < 2; ++n) _Pragma("unroll") for (int k = 0; k < 2; ++k) dst[n][k] = *(const PG8_LAS bf16x8*)(lds + PG8_SB(b, h) + boff + n * 2048 + k * 1024); } while (0)
; #define PG8_MMA(ai, bj, At, Bt) do { __builtin_amdgcn_s_setprio(1); _Pragma("unroll") for (int m = 0; m < 4; ++m) _Pragma("unroll") for (int n = 0; n < 2; ++n) _Pragma("unroll") for (int k = 0; k < 2; ++k) \
;         acc[ai][bj][m][n] = __builtin_amdgcn_mfma_f32_16x16x32_bf16(Bt[n][k], At[m][k], acc[ai][bj][m][n], 0, 0, 0); __builtin_amdgcn_s_setprio(0); } while (0)
; #define PG8_WAIT_V(n) asm volatile("s_waitcnt vmcnt(" #n ")" ::: "memory")
; #define PG8_WAIT_L(n) asm volatile("s_waitcnt lgkmcnt(" #n ")" ::: "memory")
; #define PG8_BAR __builtin_amdgcn_s_barrier()
; #define PG8_SCHED __builtin_amdgcn_sched_barrier(0)
; template <class Epi, class Sched, bool ALIGN_EPI = false, bool SP2 = false>
; __device__ __forceinline__ void gemm_phase(PG8_LAS unsigned char* lds, const Gemm g, const Sched& S, const Epi& E) {
;     ...
;         for (int t = 0; t < nt; t += 2) {
;     ...
;             PG8_LDB(B0, 1, 0); PG8_LDB(B1, 1, 1); PG8_SCHED; PG8_LDA(At, 1, 0); PG8_STAGE(PG8_SA(0, 1), a2 + hstepA, voffA);
;             PG8_WAIT_V(8); PG8_WAIT_L(0); PG8_BAR; PG8_MMA(0, 0, At, B0); PG8_MMA(0, 1, At, B1); PG8_BAR; PG8_SCHED;
;             PG8_LDA(At, 1, 1); PG8_STAGE(PG8_SB(1, 0), b3, voffB); PG8_STAGE(PG8_SB(1, 1), b3 + hstepB, voffB); PG8_STAGE(PG8_SA(1, 0), a3, voffA);
;             PG8_WAIT_V(8); PG8_WAIT_L(0); PG8_BAR; PG8_MMA(1, 0, At, B0); PG8_MMA(1, 1, At, B1); PG8_BAR; PG8_SCHED;
	s_add_i32 s38, s57, s40
	v_lshl_add_u64 v[218:219], v[218:219], 0, s[12:13]
	s_mov_b32 m0, s38
	ds_read_b128 v[186:189], v178 offset:49152
	ds_read_b128 v[190:193], v178 offset:50176
	ds_read_b128 v[194:197], v178 offset:51200
	ds_read_b128 v[198:201], v178 offset:52224
	ds_read_b128 v[202:205], v178 offset:53248
	ds_read_b128 v[206:209], v178 offset:54272
	ds_read_b128 v[210:213], v178 offset:55296
	ds_read_b128 v[214:217], v178 offset:56320
	global_load_lds_dwordx4 v[218:219], off
	s_add_i32 m0, s38, 0x2000
	s_add_u32 s36, s36, 0x40080
	v_lshl_add_u64 v[218:219], v[220:221], 0, s[12:13]
	s_addc_u32 s37, s37, 0
	s_add_i32 s38, s58, s40
	global_load_lds_dwordx4 v[218:219], off
	v_lshl_add_u64 v[218:219], s[36:37], 0, v[146:147]
	s_mov_b32 m0, s38
	s_nop 0
	global_load_lds_dwordx4 v[218:219], off
	v_lshl_add_u64 v[218:219], s[36:37], 0, v[150:151]
	s_add_i32 m0, s38, 0x2000
	s_nop 0
	global_load_lds_dwordx4 v[218:219], off
	v_lshl_add_u64 v[218:219], v[222:223], 0, s[12:13]
	s_mov_b32 m0, s45
	s_nop 0
	global_load_lds_dwordx4 v[218:219], off
	v_lshl_add_u64 v[218:219], v[224:225], 0, s[12:13]
	s_mov_b32 m0, s46
	s_nop 0
	global_load_lds_dwordx4 v[218:219], off
	s_waitcnt vmcnt(8)
	s_waitcnt lgkmcnt(0)
	s_barrier
	s_setprio 1
	s_waitcnt lgkmcnt(0)
	v_mfma_f32_16x16x32_bf16 v[60:63], v[128:131], v[186:189], v[60:63]
	v_mfma_f32_16x16x32_bf16 v[56:59], v[136:139], v[186:189], v[56:59]
	v_mfma_f32_16x16x32_bf16 v[44:47], v[128:131], v[194:197], v[44:47]
	v_mfma_f32_16x16x32_bf16 v[40:43], v[136:139], v[194:197], v[40:43]
	v_mfma_f32_16x16x32_bf16 v[28:31], v[128:131], v[202:205], v[28:31]
	v_mfma_f32_16x16x32_bf16 v[24:27], v[136:139], v[202:205], v[24:27]
	v_mfma_f32_16x16x32_bf16 v[12:15], v[128:131], v[210:213], v[12:15]
	v_mfma_f32_16x16x32_bf16 v[8:11], v[136:139], v[210:213], v[8:11]
	v_mfma_f32_16x16x32_bf16 v[60:63], v[132:135], v[190:193], v[60:63]
	v_mfma_f32_16x16x32_bf16 v[56:59], v[140:143], v[190:193], v[56:59]
	v_mfma_f32_16x16x32_bf16 v[44:47], v[132:135], v[198:201], v[44:47]
	v_mfma_f32_16x16x32_bf16 v[40:43], v[140:143], v[198:201], v[40:43]
	v_mfma_f32_16x16x32_bf16 v[28:31], v[132:135], v[206:209], v[28:31]
	v_mfma_f32_16x16x32_bf16 v[24:27], v[140:143], v[206:209], v[24:27]
	v_mfma_f32_16x16x32_bf16 v[12:15], v[132:135], v[214:217], v[12:15]
	v_mfma_f32_16x16x32_bf16 v[8:11], v[140:143], v[214:217], v[8:11]
	v_mfma_f32_16x16x32_bf16 v[52:55], v[162:165], v[186:189], v[52:55]
	v_mfma_f32_16x16x32_bf16 v[48:51], v[170:173], v[186:189], v[48:51]
	v_mfma_f32_16x16x32_bf16 v[36:39], v[162:165], v[194:197], v[36:39]
	v_mfma_f32_16x16x32_bf16 v[32:35], v[170:173], v[194:197], v[32:35]
	v_mfma_f32_16x16x32_bf16 v[20:23], v[162:165], v[202:205], v[20:23]
	v_mfma_f32_16x16x32_bf16 v[16:19], v[170:173], v[202:205], v[16:19]
	v_mfma_f32_16x16x32_bf16 v[4:7], v[162:165], v[210:213], v[4:7]
	v_mfma_f32_16x16x32_bf16 v[0:3], v[170:173], v[210:213], v[0:3]
	v_mfma_f32_16x16x32_bf16 v[52:55], v[166:169], v[190:193], v[52:55]
	v_mfma_f32_16x16x32_bf16 v[48:51], v[180:183], v[190:193], v[48:51]
	v_mfma_f32_16x16x32_bf16 v[36:39], v[166:169], v[198:201], v[36:39]
	v_mfma_f32_16x16x32_bf16 v[32:35], v[180:183], v[198:201], v[32:35]
	v_mfma_f32_16x16x32_bf16 v[20:23], v[166:169], v[206:209], v[20:23]
	v_mfma_f32_16x16x32_bf16 v[16:19], v[180:183], v[206:209], v[16:19]
	v_mfma_f32_16x16x32_bf16 v[4:7], v[166:169], v[214:217], v[4:7]
	v_mfma_f32_16x16x32_bf16 v[0:3], v[180:183], v[214:217], v[0:3]
	s_setprio 0
	s_barrier
	s_add_i32 s56, s56, 2
	s_add_u32 s34, s34, 0x100
	s_addc_u32 s35, s35, 0
	s_add_u32 s54, s54, 0x100
	s_addc_u32 s55, s55, 0
	s_cmp_gt_u32 s56, 13
	s_cbranch_scc0 .LBB0_1007
	s_and_b64 vcc, exec, s[16:17]
	s_cbranch_vccz .LBB0_1010
	s_barrier

; #define PG8_STAGE(bufoff, gbase, voff) do { _Pragma("unroll") for (int _i = 0; _i < 2; ++_i) \
;         __builtin_amdgcn_global_load_lds((const unsigned*)((const char*)(gbase) + (voff)[_i]), (PG8_LAS unsigned*)(lds + (bufoff) + ldsw + _i * 8192), 16, 0, 0); } while (0)
; #define PG8_LDA(dst, b, h) do { _Pragma("unroll") for (int m = 0; m < 4; ++m) _Pragma("unroll") for (int k = 0; k < 2; ++k) dst[m][k] = *(const PG8_LAS bf16x8*)(lds + PG8_SA(b, h) + aoff + m * 2048 + k * 1024); } while (0)
; #define PG8_LDB(dst, b, h) do { _Pragma("unroll") for (int n = 0; n < 2; ++n) _Pragma("unroll") for (int k = 0; k < 2; ++k) dst[n][k] = *(const PG8_LAS bf16x8*)(lds + PG8_SB(b, h) + boff + n * 2048 + k * 1024); } while (0)
; #define PG8_MMA(ai, bj, At, Bt) do { __builtin_amdgcn_s_setprio(1); _Pragma("unroll") for (int m = 0; m < 4; ++m) _Pragma("unroll") for (int n = 0; n < 2; ++n) _Pragma("unroll") for (int k = 0; k < 2; ++k) \
;         acc[ai][bj][m][n] = __builtin_amdgcn_mfma_f32_16x16x32_bf16(Bt[n][k], At[m][k], acc[ai][bj][m][n], 0, 0, 0); __builtin_amdgcn_s_setprio(0); } while (0)
; #define PG8_WAIT_V(n) asm volatile("s_waitcnt vmcnt(" #n ")" ::: "memory")
; #define PG8_WAIT_L(n) asm volatile("s_waitcnt lgkmcnt(" #n ")" ::: "memory")
; #define PG8_BAR __builtin_amdgcn_s_barrier()
; #define PG8_SCHED __builtin_amdgcn_sched_barrier(0)
; template <class Epi, class Sched, bool ALIGN_EPI = false, bool SP2 = false>
; __device__ __forceinline__ void gemm_phase(PG8_LAS unsigned char* lds, const Gemm g, const Sched& S, const Epi& E) {
;     ...
;             PG8_LDB(B0, 0, 0); PG8_LDB(B1, 0, 1); PG8_SCHED; PG8_LDA(At, 0, 0); PG8_STAGE(PG8_SA(1, 1), a1 + hstepA, voffA);
;             PG8_WAIT_V(8); PG8_WAIT_L(0); PG8_BAR; PG8_MMA(0, 0, At, B0); PG8_MMA(0, 1, At, B1); PG8_BAR; PG8_SCHED;
;             PG8_LDA(At, 0, 1); PG8_STAGE(PG8_SB(0, 0), b2, voffB); PG8_STAGE(PG8_SB(0, 1), b2 + hstepB, voffB); PG8_STAGE(PG8_SA(0, 0), a2, voffA);
;             PG8_WAIT_V(8); PG8_WAIT_L(0); PG8_BAR; PG8_MMA(1, 0, At, B0); PG8_MMA(1, 1, At, B1); PG8_BAR; PG8_SCHED;
.LBB0_1061:
	ds_read_b128 v[128:131], v199
	ds_read_b128 v[132:135], v199 offset:1024
	ds_read_b128 v[136:139], v199 offset:2048
	ds_read_b128 v[140:143], v199 offset:3072
	ds_read_b128 v[144:147], v200
	ds_read_b128 v[148:151], v200 offset:1024
	ds_read_b128 v[152:155], v200 offset:2048
	ds_read_b128 v[156:159], v200 offset:3072
	s_add_u32 s20, s18, 0xfff00080
	s_addc_u32 s21, s19, -1
	s_cmp_eq_u32 s45, 60
	s_cselect_b32 s23, s11, s21
	s_cselect_b32 s22, s41, s20
	s_cselect_b32 s21, s9, s44
	s_cselect_b32 s20, s42, s43
	v_lshl_add_u64 v[196:197], s[18:19], 0, v[180:181]
	s_add_i32 m0, s17, 0xc000
	ds_read_b128 v[160:163], v201
	ds_read_b128 v[164:167], v201 offset:1024
	ds_read_b128 v[188:191], v201 offset:2048
	ds_read_b128 v[192:195], v201 offset:3072
	ds_read_b128 v[202:205], v201 offset:4096
	ds_read_b128 v[206:209], v201 offset:5120
	ds_read_b128 v[210:213], v201 offset:6144
	ds_read_b128 v[214:217], v201 offset:7168
	global_load_lds_dwordx4 v[196:197], off
	v_lshl_add_u64 v[196:197], s[18:19], 0, v[182:183]
	s_add_i32 m0, s17, 0xe000
	s_nop 0
	global_load_lds_dwordx4 v[196:197], off
	s_waitcnt vmcnt(8)
	s_waitcnt lgkmcnt(0)
	s_barrier
	s_setprio 1
	s_waitcnt lgkmcnt(0)
	v_mfma_f32_16x16x32_bf16 v[124:127], v[128:131], v[160:163], v[124:127]
	v_mfma_f32_16x16x32_bf16 v[120:123], v[136:139], v[160:163], v[120:123]
	v_mfma_f32_16x16x32_bf16 v[112:115], v[128:131], v[188:191], v[112:115]
	v_mfma_f32_16x16x32_bf16 v[104:107], v[136:139], v[188:191], v[104:107]
	v_mfma_f32_16x16x32_bf16 v[96:99], v[128:131], v[202:205], v[96:99]
	v_mfma_f32_16x16x32_bf16 v[88:91], v[136:139], v[202:205], v[88:91]
	v_mfma_f32_16x16x32_bf16 v[80:83], v[128:131], v[210:213], v[80:83]
	v_mfma_f32_16x16x32_bf16 v[72:75], v[136:139], v[210:213], v[72:75]
	v_mfma_f32_16x16x32_bf16 v[124:127], v[132:135], v[164:167], v[124:127]
	v_mfma_f32_16x16x32_bf16 v[120:123], v[140:143], v[164:167], v[120:123]
	v_mfma_f32_16x16x32_bf16 v[112:115], v[132:135], v[192:195], v[112:115]
	v_mfma_f32_16x16x32_bf16 v[104:107], v[140:143], v[192:195], v[104:107]
	v_mfma_f32_16x16x32_bf16 v[96:99], v[132:135], v[206:209], v[96:99]
	v_mfma_f32_16x16x32_bf16 v[88:91], v[140:143], v[206:209], v[88:91]
	v_mfma_f32_16x16x32_bf16 v[80:83], v[132:135], v[214:217], v[80:83]
	v_mfma_f32_16x16x32_bf16 v[72:75], v[140:143], v[214:217], v[72:75]
	v_mfma_f32_16x16x32_bf16 v[116:119], v[144:147], v[160:163], v[116:119]
	v_mfma_f32_16x16x32_bf16 v[108:111], v[152:155], v[160:163], v[108:111]
	v_mfma_f32_16x16x32_bf16 v[100:103], v[144:147], v[188:191], v[100:103]
	v_mfma_f32_16x16x32_bf16 v[92:95], v[152:155], v[188:191], v[92:95]
	v_mfma_f32_16x16x32_bf16 v[84:87], v[144:147], v[202:205], v[84:87]
	v_mfma_f32_16x16x32_bf16 v[76:79], v[152:155], v[202:205], v[76:79]
	v_mfma_f32_16x16x32_bf16 v[68:71], v[144:147], v[210:213], v[68:71]
	v_mfma_f32_16x16x32_bf16 v[64:67], v[152:155], v[210:213], v[64:67]
	v_mfma_f32_16x16x32_bf16 v[116:119], v[148:151], v[164:167], v[116:119]
	v_mfma_f32_16x16x32_bf16 v[108:111], v[156:159], v[164:167], v[108:111]
	v_mfma_f32_16x16x32_bf16 v[100:103], v[148:151], v[192:195], v[100:103]
	v_mfma_f32_16x16x32_bf16 v[92:95], v[156:159], v[192:195], v[92:95]
	v_mfma_f32_16x16x32_bf16 v[84:87], v[148:151], v[206:209], v[84:87]
	v_mfma_f32_16x16x32_bf16 v[76:79], v[156:159], v[206:209], v[76:79]
	v_mfma_f32_16x16x32_bf16 v[68:71], v[148:151], v[214:217], v[68:71]
	v_mfma_f32_16x16x32_bf16 v[64:67], v[156:159], v[214:217], v[64:67]
	s_setprio 0
	s_barrier
	s_add_i32 s46, s38, s29
	v_lshl_add_u64 v[196:197], s[20:21], 0, v[170:171]
	s_mov_b32 m0, s46
	ds_read_b128 v[160:163], v201 offset:16384
	ds_read_b128 v[164:167], v201 offset:17408
	ds_read_b128 v[188:191], v201 offset:18432
	ds_read_b128 v[192:195], v201 offset:19456
	ds_read_b128 v[202:205], v201 offset:20480
	ds_read_b128 v[206:209], v201 offset:21504
	ds_read_b128 v[210:213], v201 offset:22528
	ds_read_b128 v[214:217], v201 offset:23552
	global_load_lds_dwordx4 v[196:197], off
	s_add_i32 m0, s46, 0x2000
	s_add_u32 s46, s20, 0x100000
	v_lshl_add_u64 v[218:219], s[20:21], 0, v[174:175]
	s_addc_u32 s47, s21, 0
	s_add_i32 s48, s39, s29
	global_load_lds_dwordx4 v[218:219], off
	v_lshl_add_u64 v[220:221], s[46:47], 0, v[170:171]
	s_mov_b32 m0, s48
	v_lshl_add_u64 v[222:223], s[22:23], 0, v[172:173]
	global_load_lds_dwordx4 v[220:221], off
	v_lshl_add_u64 v[220:221], s[46:47], 0, v[174:175]
	s_add_i32 m0, s48, 0x2000
	s_nop 0
	global_load_lds_dwordx4 v[220:221], off
	v_lshl_add_u64 v[220:221], s[22:23], 0, v[168:169]
	s_mov_b32 m0, s17
	s_nop 0
	global_load_lds_dwordx4 v[220:221], off
	s_mov_b32 m0, s30
	s_nop 0
	global_load_lds_dwordx4 v[222:223], off
	s_waitcnt vmcnt(8)
	s_waitcnt lgkmcnt(0)
	s_barrier
; #define PG8_STAGE(bufoff, gbase, voff) do { _Pragma("unroll") for (int _i = 0; _i < 2; ++_i) \
;         __builtin_amdgcn_global_load_lds((const unsigned*)((const char*)(gbase) + (voff)[_i]), (PG8_LAS unsigned*)(lds + (bufoff) + ldsw + _i * 8192), 16, 0, 0); } while (0)
; #define PG8_LDA(dst, b, h) do { _Pragma("unroll") for (int m = 0; m < 4; ++m) _Pragma("unroll") for (int k = 0; k < 2; ++k) dst[m][k] = *(const PG8_LAS bf16x8*)(lds + PG8_SA(b, h) + aoff + m * 2048 + k * 1024); } while (0)
; #define PG8_LDB(dst, b, h) do { _Pragma("unroll") for (int n = 0; n < 2; ++n) _Pragma("unroll") for (int k = 0; k < 2; ++k) dst[n][k] = *(const PG8_LAS bf16x8*)(lds + PG8_SB(b, h) + boff + n * 2048 + k * 1024); } while (0)
; #define PG8_MMA(ai, bj, At, Bt) do { __builtin_amdgcn_s_setprio(1); _Pragma("unroll") for (int m = 0; m < 4; ++m) _Pragma("unroll") for (int n = 0; n < 2; ++n) _Pragma("unroll") for (int k = 0; k < 2; ++k) \
;         acc[ai][bj][m][n] = __builtin_amdgcn_mfma_f32_16x16x32_bf16(Bt[n][k], At[m][k], acc[ai][bj][m][n], 0, 0, 0); __builtin_amdgcn_s_setprio(0); } while (0)
; #define PG8_WAIT_V(n) asm volatile("s_waitcnt vmcnt(" #n ")" ::: "memory")
; #define PG8_WAIT_L(n) asm volatile("s_waitcnt lgkmcnt(" #n ")" ::: "memory")
; #define PG8_BAR __builtin_amdgcn_s_barrier()
; #define PG8_SCHED __builtin_amdgcn_sched_barrier(0)
; template <class Epi, class Sched, bool ALIGN_EPI = false, bool SP2 = false>
; __device__ __forceinline__ void gemm_phase(PG8_LAS unsigned char* lds, const Gemm g, const Sched& S, const Epi& E) {
;     ...
;             PG8_LDA(At, 0, 1); PG8_STAGE(PG8_SB(0, 0), b2, voffB); PG8_STAGE(PG8_SB(0, 1), b2 + hstepB, voffB); PG8_STAGE(PG8_SA(0, 0), a2, voffA);
;             PG8_WAIT_V(8); PG8_WAIT_L(0); PG8_BAR; PG8_MMA(1, 0, At, B0); PG8_MMA(1, 1, At, B1); PG8_BAR; PG8_SCHED;
;             PG8_LDB(B0, 1, 0); PG8_LDB(B1, 1, 1); PG8_SCHED; PG8_LDA(At, 1, 0); PG8_STAGE(PG8_SA(0, 1), a2 + hstepA, voffA);
;             PG8_WAIT_V(8); PG8_WAIT_L(0); PG8_BAR; PG8_MMA(0, 0, At, B0); PG8_MMA(0, 1, At, B1); PG8_BAR; PG8_SCHED;
	s_setprio 1
	s_waitcnt lgkmcnt(0)
	v_mfma_f32_16x16x32_bf16 v[60:63], v[128:131], v[160:163], v[60:63]
	v_mfma_f32_16x16x32_bf16 v[56:59], v[136:139], v[160:163], v[56:59]
	v_mfma_f32_16x16x32_bf16 v[48:51], v[128:131], v[188:191], v[48:51]
	v_mfma_f32_16x16x32_bf16 v[40:43], v[136:139], v[188:191], v[40:43]
	v_mfma_f32_16x16x32_bf16 v[32:35], v[128:131], v[202:205], v[32:35]
	v_mfma_f32_16x16x32_bf16 v[24:27], v[136:139], v[202:205], v[24:27]
	v_mfma_f32_16x16x32_bf16 v[16:19], v[128:131], v[210:213], v[16:19]
	v_mfma_f32_16x16x32_bf16 v[8:11], v[136:139], v[210:213], v[8:11]
	v_mfma_f32_16x16x32_bf16 v[60:63], v[132:135], v[164:167], v[60:63]
	v_mfma_f32_16x16x32_bf16 v[56:59], v[140:143], v[164:167], v[56:59]
	v_mfma_f32_16x16x32_bf16 v[48:51], v[132:135], v[192:195], v[48:51]
	v_mfma_f32_16x16x32_bf16 v[40:43], v[140:143], v[192:195], v[40:43]
	v_mfma_f32_16x16x32_bf16 v[32:35], v[132:135], v[206:209], v[32:35]
	v_mfma_f32_16x16x32_bf16 v[24:27], v[140:143], v[206:209], v[24:27]
	v_mfma_f32_16x16x32_bf16 v[16:19], v[132:135], v[214:217], v[16:19]
	v_mfma_f32_16x16x32_bf16 v[8:11], v[140:143], v[214:217], v[8:11]
	v_mfma_f32_16x16x32_bf16 v[52:55], v[144:147], v[160:163], v[52:55]
	v_mfma_f32_16x16x32_bf16 v[44:47], v[152:155], v[160:163], v[44:47]
	v_mfma_f32_16x16x32_bf16 v[36:39], v[144:147], v[188:191], v[36:39]
	v_mfma_f32_16x16x32_bf16 v[28:31], v[152:155], v[188:191], v[28:31]
	v_mfma_f32_16x16x32_bf16 v[20:23], v[144:147], v[202:205], v[20:23]
	v_mfma_f32_16x16x32_bf16 v[12:15], v[152:155], v[202:205], v[12:15]
	v_mfma_f32_16x16x32_bf16 v[4:7], v[144:147], v[210:213], v[4:7]
	v_mfma_f32_16x16x32_bf16 v[0:3], v[152:155], v[210:213], v[0:3]
	v_mfma_f32_16x16x32_bf16 v[52:55], v[148:151], v[164:167], v[52:55]
	v_mfma_f32_16x16x32_bf16 v[44:47], v[156:159], v[164:167], v[44:47]
	v_mfma_f32_16x16x32_bf16 v[36:39], v[148:151], v[192:195], v[36:39]
	v_mfma_f32_16x16x32_bf16 v[28:31], v[156:159], v[192:195], v[28:31]
	v_mfma_f32_16x16x32_bf16 v[20:23], v[148:151], v[206:209], v[20:23]
	v_mfma_f32_16x16x32_bf16 v[12:15], v[156:159], v[206:209], v[12:15]
	v_mfma_f32_16x16x32_bf16 v[4:7], v[148:151], v[214:217], v[4:7]
	v_mfma_f32_16x16x32_bf16 v[0:3], v[156:159], v[214:217], v[0:3]
	s_setprio 0
	s_barrier
	s_add_i32 s46, 0, 0x18000
	s_add_i32 s47, 0, 0x1c000
	v_add_u32_e32 v140, s46, v198
	v_add_u32_e32 v156, s47, v198
	ds_read_b128 v[128:131], v140
	ds_read_b128 v[132:135], v140 offset:1024
	ds_read_b128 v[136:139], v140 offset:2048
	ds_read_b128 v[140:143], v140 offset:3072
	ds_read_b128 v[144:147], v156
	ds_read_b128 v[148:151], v156 offset:1024
	ds_read_b128 v[152:155], v156 offset:2048
	ds_read_b128 v[156:159], v156 offset:3072
	s_add_u32 s22, s22, 0x100000
	s_addc_u32 s23, s23, 0
	s_mov_b32 m0, s31
	v_lshl_add_u64 v[224:225], s[22:23], 0, v[168:169]
	ds_read_b128 v[160:163], v201 offset:32768
	ds_read_b128 v[164:167], v201 offset:33792
	ds_read_b128 v[188:191], v201 offset:34816
	ds_read_b128 v[192:195], v201 offset:35840
	ds_read_b128 v[202:205], v201 offset:36864
	ds_read_b128 v[206:209], v201 offset:37888
	ds_read_b128 v[210:213], v201 offset:38912
	ds_read_b128 v[214:217], v201 offset:39936
	global_load_lds_dwordx4 v[224:225], off
	v_lshl_add_u64 v[224:225], s[22:23], 0, v[172:173]
	s_mov_b32 m0, s33
	s_nop 0
	global_load_lds_dwordx4 v[224:225], off
	s_waitcnt vmcnt(8)
	s_waitcnt lgkmcnt(0)
	s_barrier
	s_setprio 1
	s_waitcnt lgkmcnt(0)
	v_mfma_f32_16x16x32_bf16 v[124:127], v[128:131], v[160:163], v[124:127]
	v_mfma_f32_16x16x32_bf16 v[120:123], v[136:139], v[160:163], v[120:123]
	v_mfma_f32_16x16x32_bf16 v[112:115], v[128:131], v[188:191], v[112:115]
	v_mfma_f32_16x16x32_bf16 v[104:107], v[136:139], v[188:191], v[104:107]
	v_mfma_f32_16x16x32_bf16 v[96:99], v[128:131], v[202:205], v[96:99]
	v_mfma_f32_16x16x32_bf16 v[88:91], v[136:139], v[202:205], v[88:91]
	v_mfma_f32_16x16x32_bf16 v[80:83], v[128:131], v[210:213], v[80:83]
	v_mfma_f32_16x16x32_bf16 v[72:75], v[136:139], v[210:213], v[72:75]
	v_mfma_f32_16x16x32_bf16 v[124:127], v[132:135], v[164:167], v[124:127]
	v_mfma_f32_16x16x32_bf16 v[120:123], v[140:143], v[164:167], v[120:123]
	v_mfma_f32_16x16x32_bf16 v[112:115], v[132:135], v[192:195], v[112:115]
	v_mfma_f32_16x16x32_bf16 v[104:107], v[140:143], v[192:195], v[104:107]
	v_mfma_f32_16x16x32_bf16 v[96:99], v[132:135], v[206:209], v[96:99]
	v_mfma_f32_16x16x32_bf16 v[88:91], v[140:143], v[206:209], v[88:91]
	v_mfma_f32_16x16x32_bf16 v[80:83], v[132:135], v[214:217], v[80:83]
	v_mfma_f32_16x16x32_bf16 v[72:75], v[140:143], v[214:217], v[72:75]
	v_mfma_f32_16x16x32_bf16 v[116:119], v[144:147], v[160:163], v[116:119]
	v_mfma_f32_16x16x32_bf16 v[108:111], v[152:155], v[160:163], v[108:111]
	v_mfma_f32_16x16x32_bf16 v[100:103], v[144:147], v[188:191], v[100:103]
	v_mfma_f32_16x16x32_bf16 v[92:95], v[152:155], v[188:191], v[92:95]
	v_mfma_f32_16x16x32_bf16 v[84:87], v[144:147], v[202:205], v[84:87]
	v_mfma_f32_16x16x32_bf16 v[76:79], v[152:155], v[202:205], v[76:79]
	v_mfma_f32_16x16x32_bf16 v[68:71], v[144:147], v[210:213], v[68:71]
	v_mfma_f32_16x16x32_bf16 v[64:67], v[152:155], v[210:213], v[64:67]
	v_mfma_f32_16x16x32_bf16 v[116:119], v[148:151], v[164:167], v[116:119]
	v_mfma_f32_16x16x32_bf16 v[108:111], v[156:159], v[164:167], v[108:111]
	v_mfma_f32_16x16x32_bf16 v[100:103], v[148:151], v[192:195], v[100:103]
	v_mfma_f32_16x16x32_bf16 v[92:95], v[156:159], v[192:195], v[92:95]
	v_mfma_f32_16x16x32_bf16 v[84:87], v[148:151], v[206:209], v[84:87]
	v_mfma_f32_16x16x32_bf16 v[76:79], v[156:159], v[206:209], v[76:79]
	v_mfma_f32_16x16x32_bf16 v[68:71], v[148:151], v[214:217], v[68:71]
	v_mfma_f32_16x16x32_bf16 v[64:67], v[156:159], v[214:217], v[64:67]
	s_setprio 0
	s_barrier
; #define PG8_STAGE(bufoff, gbase, voff) do { _Pragma("unroll") for (int _i = 0; _i < 2; ++_i) \
;         __builtin_amdgcn_global_load_lds((const unsigned*)((const char*)(gbase) + (voff)[_i]), (PG8_LAS unsigned*)(lds + (bufoff) + ldsw + _i * 8192), 16, 0, 0); } while (0)
; #define PG8_LDA(dst, b, h) do { _Pragma("unroll") for (int m = 0; m < 4; ++m) _Pragma("unroll") for (int k = 0; k < 2; ++k) dst[m][k] = *(const PG8_LAS bf16x8*)(lds + PG8_SA(b, h) + aoff + m * 2048 + k * 1024); } while (0)
; #define PG8_LDB(dst, b, h) do { _Pragma("unroll") for (int n = 0; n < 2; ++n) _Pragma("unroll") for (int k = 0; k < 2; ++k) dst[n][k] = *(const PG8_LAS bf16x8*)(lds + PG8_SB(b, h) + boff + n * 2048 + k * 1024); } while (0)
; #define PG8_MMA(ai, bj, At, Bt) do { __builtin_amdgcn_s_setprio(1); _Pragma("unroll") for (int m = 0; m < 4; ++m) _Pragma("unroll") for (int n = 0; n < 2; ++n) _Pragma("unroll") for (int k = 0; k < 2; ++k) \
;         acc[ai][bj][m][n] = __builtin_amdgcn_mfma_f32_16x16x32_bf16(Bt[n][k], At[m][k], acc[ai][bj][m][n], 0, 0, 0); __builtin_amdgcn_s_setprio(0); } while (0)
; #define PG8_WAIT_V(n) asm volatile("s_waitcnt vmcnt(" #n ")" ::: "memory")
; #define PG8_WAIT_L(n) asm volatile("s_waitcnt lgkmcnt(" #n ")" ::: "memory")
; #define PG8_BAR __builtin_amdgcn_s_barrier()
; #define PG8_SCHED __builtin_amdgcn_sched_barrier(0)
; template <class Epi, class Sched, bool ALIGN_EPI = false, bool SP2 = false>
; __device__ __forceinline__ void gemm_phase(PG8_LAS unsigned char* lds, const Gemm g, const Sched& S, const Epi& E) {
;     ...
;         for (int t = 0; t < nt; t += 2) {
;     ...
;             PG8_LDB(B0, 1, 0); PG8_LDB(B1, 1, 1); PG8_SCHED; PG8_LDA(At, 1, 0); PG8_STAGE(PG8_SA(0, 1), a2 + hstepA, voffA);
;             PG8_WAIT_V(8); PG8_WAIT_L(0); PG8_BAR; PG8_MMA(0, 0, At, B0); PG8_MMA(0, 1, At, B1); PG8_BAR; PG8_SCHED;
;             PG8_LDA(At, 1, 1); PG8_STAGE(PG8_SB(1, 0), b3, voffB); PG8_STAGE(PG8_SB(1, 1), b3 + hstepB, voffB); PG8_STAGE(PG8_SA(1, 0), a3, voffA);
;             PG8_WAIT_V(8); PG8_WAIT_L(0); PG8_BAR; PG8_MMA(1, 0, At, B0); PG8_MMA(1, 1, At, B1); PG8_BAR; PG8_SCHED;
	s_add_i32 s22, s46, s29
	v_lshl_add_u64 v[196:197], v[196:197], 0, s[4:5]
	s_mov_b32 m0, s22
	ds_read_b128 v[160:163], v201 offset:49152
	ds_read_b128 v[164:167], v201 offset:50176
	ds_read_b128 v[188:191], v201 offset:51200
	ds_read_b128 v[192:195], v201 offset:52224
	ds_read_b128 v[202:205], v201 offset:53248
	ds_read_b128 v[206:209], v201 offset:54272
	ds_read_b128 v[210:213], v201 offset:55296
	ds_read_b128 v[214:217], v201 offset:56320
	global_load_lds_dwordx4 v[196:197], off
	s_add_i32 m0, s22, 0x2000
	s_add_u32 s20, s20, 0x100080
	v_lshl_add_u64 v[196:197], v[218:219], 0, s[4:5]
	s_addc_u32 s21, s21, 0
	s_add_i32 s22, s47, s29
	global_load_lds_dwordx4 v[196:197], off
	v_lshl_add_u64 v[196:197], s[20:21], 0, v[170:171]
	s_mov_b32 m0, s22
	s_nop 0
	global_load_lds_dwordx4 v[196:197], off
	v_lshl_add_u64 v[196:197], s[20:21], 0, v[174:175]
	s_add_i32 m0, s22, 0x2000
	s_nop 0
	global_load_lds_dwordx4 v[196:197], off
	v_lshl_add_u64 v[196:197], v[220:221], 0, s[4:5]
	s_mov_b32 m0, s35
	s_nop 0
	global_load_lds_dwordx4 v[196:197], off
	v_lshl_add_u64 v[196:197], v[222:223], 0, s[4:5]
	s_mov_b32 m0, s36
	s_nop 0
	global_load_lds_dwordx4 v[196:197], off
	s_waitcnt vmcnt(8)
	s_waitcnt lgkmcnt(0)
	s_barrier
	s_setprio 1
	s_waitcnt lgkmcnt(0)
	v_mfma_f32_16x16x32_bf16 v[60:63], v[128:131], v[160:163], v[60:63]
	v_mfma_f32_16x16x32_bf16 v[56:59], v[136:139], v[160:163], v[56:59]
	v_mfma_f32_16x16x32_bf16 v[48:51], v[128:131], v[188:191], v[48:51]
	v_mfma_f32_16x16x32_bf16 v[40:43], v[136:139], v[188:191], v[40:43]
	v_mfma_f32_16x16x32_bf16 v[32:35], v[128:131], v[202:205], v[32:35]
	v_mfma_f32_16x16x32_bf16 v[24:27], v[136:139], v[202:205], v[24:27]
	v_mfma_f32_16x16x32_bf16 v[16:19], v[128:131], v[210:213], v[16:19]
	v_mfma_f32_16x16x32_bf16 v[8:11], v[136:139], v[210:213], v[8:11]
	v_mfma_f32_16x16x32_bf16 v[60:63], v[132:135], v[164:167], v[60:63]
	v_mfma_f32_16x16x32_bf16 v[56:59], v[140:143], v[164:167], v[56:59]
	v_mfma_f32_16x16x32_bf16 v[48:51], v[132:135], v[192:195], v[48:51]
	v_mfma_f32_16x16x32_bf16 v[40:43], v[140:143], v[192:195], v[40:43]
	v_mfma_f32_16x16x32_bf16 v[32:35], v[132:135], v[206:209], v[32:35]
	v_mfma_f32_16x16x32_bf16 v[24:27], v[140:143], v[206:209], v[24:27]
	v_mfma_f32_16x16x32_bf16 v[16:19], v[132:135], v[214:217], v[16:19]
	v_mfma_f32_16x16x32_bf16 v[8:11], v[140:143], v[214:217], v[8:11]
	v_mfma_f32_16x16x32_bf16 v[52:55], v[144:147], v[160:163], v[52:55]
	v_mfma_f32_16x16x32_bf16 v[44:47], v[152:155], v[160:163], v[44:47]
	v_mfma_f32_16x16x32_bf16 v[36:39], v[144:147], v[188:191], v[36:39]
	v_mfma_f32_16x16x32_bf16 v[28:31], v[152:155], v[188:191], v[28:31]
	v_mfma_f32_16x16x32_bf16 v[20:23], v[144:147], v[202:205], v[20:23]
	v_mfma_f32_16x16x32_bf16 v[12:15], v[152:155], v[202:205], v[12:15]
	v_mfma_f32_16x16x32_bf16 v[4:7], v[144:147], v[210:213], v[4:7]
	v_mfma_f32_16x16x32_bf16 v[0:3], v[152:155], v[210:213], v[0:3]
	v_mfma_f32_16x16x32_bf16 v[52:55], v[148:151], v[164:167], v[52:55]
	v_mfma_f32_16x16x32_bf16 v[44:47], v[156:159], v[164:167], v[44:47]
	v_mfma_f32_16x16x32_bf16 v[36:39], v[148:151], v[192:195], v[36:39]
	v_mfma_f32_16x16x32_bf16 v[28:31], v[156:159], v[192:195], v[28:31]
	v_mfma_f32_16x16x32_bf16 v[20:23], v[148:151], v[206:209], v[20:23]
	v_mfma_f32_16x16x32_bf16 v[12:15], v[156:159], v[206:209], v[12:15]
	v_mfma_f32_16x16x32_bf16 v[4:7], v[148:151], v[214:217], v[4:7]
	v_mfma_f32_16x16x32_bf16 v[0:3], v[156:159], v[214:217], v[0:3]
	s_setprio 0
	s_barrier
	s_add_i32 s45, s45, 2
	s_add_u32 s18, s18, 0x100
	s_addc_u32 s19, s19, 0
	s_add_u32 s43, s43, 0x100
	s_addc_u32 s44, s44, 0
	s_cmp_gt_u32 s45, 61
	s_cbranch_scc0 .LBB0_1061
	s_and_b64 vcc, exec, s[6:7]
	s_cbranch_vccz .LBB0_1064
	s_barrier
